# one s_barrier per MFMA block with per-half duplicated loop bodies, on top of k-snake MFMA order and scalar-base DMA addressing
# baseline (speedup 1.0000x reference)
.LBB0_169:
	s_add_u32 s34, s50, 0xfff80080
	s_addc_u32 s35, s51, -1
	s_add_i32 s52, 0, 0x10000
	s_cmp_eq_u32 s77, 28
	s_cselect_b32 s55, s36, s35
	s_cselect_b32 s54, s37, s34
	v_add_u32_e32 v145, s52, v142
	s_cselect_b32 s35, s41, s76
	s_cselect_b32 s34, s43, s71
	s_add_i32 s53, 0, 0x14000
	ds_read_b128 v[146:149], v145
	ds_read_b128 v[150:153], v145 offset:1024
	ds_read_b128 v[172:175], v145 offset:2048
	ds_read_b128 v[176:179], v145 offset:3072
	v_add_u32_e32 v145, s53, v142
	ds_read_b128 v[180:183], v145
	ds_read_b128 v[184:187], v145 offset:1024
	ds_read_b128 v[188:191], v145 offset:2048
	ds_read_b128 v[192:195], v145 offset:3072
	s_add_i32 m0, s57, 0xc000
	ds_read_b128 v[196:199], v144
	ds_read_b128 v[200:203], v144 offset:1024
	ds_read_b128 v[204:207], v144 offset:2048
	ds_read_b128 v[208:211], v144 offset:3072
	ds_read_b128 v[212:215], v144 offset:4096
	ds_read_b128 v[216:219], v144 offset:5120
	ds_read_b128 v[228:231], v144 offset:6144
	ds_read_b128 v[232:235], v144 offset:7168
	global_load_lds_dwordx4 v138, s[50:51]
	s_add_i32 m0, s57, 0xe000
	s_nop 0
	global_load_lds_dwordx4 v140, s[50:51]
	s_waitcnt lgkmcnt(0)
	s_setprio 1
	v_mfma_f32_16x16x32_bf16 v[128:131], v[146:149], v[196:199], v[128:131]
	v_mfma_f32_16x16x32_bf16 v[128:131], v[150:153], v[200:203], v[128:131]
	v_mfma_f32_16x16x32_bf16 v[124:127], v[176:179], v[200:203], v[124:127]
	v_mfma_f32_16x16x32_bf16 v[124:127], v[172:175], v[196:199], v[124:127]
	v_mfma_f32_16x16x32_bf16 v[108:111], v[172:175], v[204:207], v[108:111]
	v_mfma_f32_16x16x32_bf16 v[108:111], v[176:179], v[208:211], v[108:111]
	v_mfma_f32_16x16x32_bf16 v[112:115], v[150:153], v[208:211], v[112:115]
	v_mfma_f32_16x16x32_bf16 v[112:115], v[146:149], v[204:207], v[112:115]
	v_mfma_f32_16x16x32_bf16 v[96:99], v[146:149], v[212:215], v[96:99]
	v_mfma_f32_16x16x32_bf16 v[96:99], v[150:153], v[216:219], v[96:99]
	v_mfma_f32_16x16x32_bf16 v[92:95], v[176:179], v[216:219], v[92:95]
	v_mfma_f32_16x16x32_bf16 v[92:95], v[172:175], v[212:215], v[92:95]
	v_mfma_f32_16x16x32_bf16 v[76:79], v[172:175], v[228:231], v[76:79]
	v_mfma_f32_16x16x32_bf16 v[76:79], v[176:179], v[232:235], v[76:79]
	v_mfma_f32_16x16x32_bf16 v[80:83], v[150:153], v[232:235], v[80:83]
	v_mfma_f32_16x16x32_bf16 v[80:83], v[146:149], v[228:231], v[80:83]
	v_mfma_f32_16x16x32_bf16 v[120:123], v[180:183], v[196:199], v[120:123]
	v_mfma_f32_16x16x32_bf16 v[120:123], v[184:187], v[200:203], v[120:123]
	v_mfma_f32_16x16x32_bf16 v[116:119], v[192:195], v[200:203], v[116:119]
	v_mfma_f32_16x16x32_bf16 v[116:119], v[188:191], v[196:199], v[116:119]
	v_mfma_f32_16x16x32_bf16 v[100:103], v[188:191], v[204:207], v[100:103]
	v_mfma_f32_16x16x32_bf16 v[100:103], v[192:195], v[208:211], v[100:103]
	v_mfma_f32_16x16x32_bf16 v[104:107], v[184:187], v[208:211], v[104:107]
	v_mfma_f32_16x16x32_bf16 v[104:107], v[180:183], v[204:207], v[104:107]
	v_mfma_f32_16x16x32_bf16 v[88:91], v[180:183], v[212:215], v[88:91]
	v_mfma_f32_16x16x32_bf16 v[88:91], v[184:187], v[216:219], v[88:91]
	v_mfma_f32_16x16x32_bf16 v[84:87], v[192:195], v[216:219], v[84:87]
	v_mfma_f32_16x16x32_bf16 v[84:87], v[188:191], v[212:215], v[84:87]
	v_mfma_f32_16x16x32_bf16 v[68:71], v[188:191], v[228:231], v[68:71]
	v_mfma_f32_16x16x32_bf16 v[68:71], v[192:195], v[232:235], v[68:71]
	v_mfma_f32_16x16x32_bf16 v[72:75], v[184:187], v[232:235], v[72:75]
	v_mfma_f32_16x16x32_bf16 v[72:75], v[180:183], v[228:231], v[72:75]
	s_waitcnt vmcnt(8)
	s_setprio 0
	s_barrier
	s_add_u32 s100, s54, s14
	s_addc_u32 s101, s55, s15
	s_add_i32 s52, s52, s19
	s_mov_b32 m0, s52
	ds_read_b128 v[196:199], v144 offset:16384
	ds_read_b128 v[200:203], v144 offset:17408
	ds_read_b128 v[204:207], v144 offset:18432
	ds_read_b128 v[208:211], v144 offset:19456
	ds_read_b128 v[212:215], v144 offset:20480
	ds_read_b128 v[216:219], v144 offset:21504
	ds_read_b128 v[228:231], v144 offset:22528
	ds_read_b128 v[232:235], v144 offset:23552
	global_load_lds_dwordx4 v134, s[34:35]
	s_add_i32 m0, s52, 0x2000
	s_add_u32 s96, s34, 0x4000
	s_addc_u32 s97, s35, 0
	s_add_i32 s52, s53, s19
	global_load_lds_dwordx4 v0, s[34:35]
	s_mov_b32 m0, s52
	s_nop 0
	global_load_lds_dwordx4 v134, s[96:97]
	s_add_i32 m0, s52, 0x2000
	s_nop 0
	global_load_lds_dwordx4 v0, s[96:97]
	s_mov_b32 m0, s57
	s_nop 0
	global_load_lds_dwordx4 v136, s[54:55]
	s_mov_b32 m0, s58
	s_nop 0
	global_load_lds_dwordx4 v132, s[54:55]
	s_waitcnt lgkmcnt(0)
	s_setprio 1
	v_mfma_f32_16x16x32_bf16 v[64:67], v[146:149], v[196:199], v[64:67]
	v_mfma_f32_16x16x32_bf16 v[64:67], v[150:153], v[200:203], v[64:67]
	v_mfma_f32_16x16x32_bf16 v[60:63], v[176:179], v[200:203], v[60:63]
	v_mfma_f32_16x16x32_bf16 v[60:63], v[172:175], v[196:199], v[60:63]
	v_mfma_f32_16x16x32_bf16 v[44:47], v[172:175], v[204:207], v[44:47]
	v_mfma_f32_16x16x32_bf16 v[44:47], v[176:179], v[208:211], v[44:47]
	v_mfma_f32_16x16x32_bf16 v[48:51], v[150:153], v[208:211], v[48:51]
	v_mfma_f32_16x16x32_bf16 v[48:51], v[146:149], v[204:207], v[48:51]
	v_mfma_f32_16x16x32_bf16 v[32:35], v[146:149], v[212:215], v[32:35]
	v_mfma_f32_16x16x32_bf16 v[32:35], v[150:153], v[216:219], v[32:35]
	v_mfma_f32_16x16x32_bf16 v[28:31], v[176:179], v[216:219], v[28:31]
	v_mfma_f32_16x16x32_bf16 v[28:31], v[172:175], v[212:215], v[28:31]
	v_mfma_f32_16x16x32_bf16 v[12:15], v[172:175], v[228:231], v[12:15]
	v_mfma_f32_16x16x32_bf16 v[12:15], v[176:179], v[232:235], v[12:15]
	v_mfma_f32_16x16x32_bf16 v[16:19], v[150:153], v[232:235], v[16:19]
	v_mfma_f32_16x16x32_bf16 v[16:19], v[146:149], v[228:231], v[16:19]
	v_mfma_f32_16x16x32_bf16 v[56:59], v[180:183], v[196:199], v[56:59]
	v_mfma_f32_16x16x32_bf16 v[56:59], v[184:187], v[200:203], v[56:59]
	v_mfma_f32_16x16x32_bf16 v[52:55], v[192:195], v[200:203], v[52:55]
	v_mfma_f32_16x16x32_bf16 v[52:55], v[188:191], v[196:199], v[52:55]
	v_mfma_f32_16x16x32_bf16 v[36:39], v[188:191], v[204:207], v[36:39]
	v_mfma_f32_16x16x32_bf16 v[36:39], v[192:195], v[208:211], v[36:39]
	v_mfma_f32_16x16x32_bf16 v[40:43], v[184:187], v[208:211], v[40:43]
	v_mfma_f32_16x16x32_bf16 v[40:43], v[180:183], v[204:207], v[40:43]
	v_mfma_f32_16x16x32_bf16 v[24:27], v[180:183], v[212:215], v[24:27]
	v_mfma_f32_16x16x32_bf16 v[24:27], v[184:187], v[216:219], v[24:27]
	v_mfma_f32_16x16x32_bf16 v[20:23], v[192:195], v[216:219], v[20:23]
	v_mfma_f32_16x16x32_bf16 v[20:23], v[188:191], v[212:215], v[20:23]
	v_mfma_f32_16x16x32_bf16 v[4:7], v[188:191], v[228:231], v[4:7]
	v_mfma_f32_16x16x32_bf16 v[4:7], v[192:195], v[232:235], v[4:7]
	v_mfma_f32_16x16x32_bf16 v[8:11], v[184:187], v[232:235], v[8:11]
	v_mfma_f32_16x16x32_bf16 v[8:11], v[180:183], v[228:231], v[8:11]
	s_waitcnt vmcnt(8)
	s_setprio 0
	s_barrier
	s_add_i32 s52, 0, 0x18000
	v_add_u32_e32 v145, s52, v142
	s_add_i32 s53, 0, 0x1c000
	ds_read_b128 v[146:149], v145
	ds_read_b128 v[150:153], v145 offset:1024
	ds_read_b128 v[172:175], v145 offset:2048
	ds_read_b128 v[176:179], v145 offset:3072
	v_add_u32_e32 v145, s53, v142
	ds_read_b128 v[180:183], v145
	ds_read_b128 v[184:187], v145 offset:1024
	ds_read_b128 v[188:191], v145 offset:2048
	ds_read_b128 v[192:195], v145 offset:3072
	s_add_u32 s54, s54, 0x80000
	s_addc_u32 s55, s55, 0
	s_mov_b32 m0, s59
	ds_read_b128 v[196:199], v144 offset:32768
	ds_read_b128 v[200:203], v144 offset:33792
	ds_read_b128 v[204:207], v144 offset:34816
	ds_read_b128 v[208:211], v144 offset:35840
	ds_read_b128 v[212:215], v144 offset:36864
	ds_read_b128 v[216:219], v144 offset:37888
	ds_read_b128 v[228:231], v144 offset:38912
	ds_read_b128 v[232:235], v144 offset:39936
	global_load_lds_dwordx4 v136, s[54:55]
	s_mov_b32 m0, s60
	s_nop 0
	global_load_lds_dwordx4 v132, s[54:55]
	s_waitcnt lgkmcnt(0)
	s_setprio 1
	v_mfma_f32_16x16x32_bf16 v[128:131], v[146:149], v[196:199], v[128:131]
	v_mfma_f32_16x16x32_bf16 v[128:131], v[150:153], v[200:203], v[128:131]
	v_mfma_f32_16x16x32_bf16 v[124:127], v[176:179], v[200:203], v[124:127]
	v_mfma_f32_16x16x32_bf16 v[124:127], v[172:175], v[196:199], v[124:127]
	v_mfma_f32_16x16x32_bf16 v[108:111], v[172:175], v[204:207], v[108:111]
	v_mfma_f32_16x16x32_bf16 v[108:111], v[176:179], v[208:211], v[108:111]
	v_mfma_f32_16x16x32_bf16 v[112:115], v[150:153], v[208:211], v[112:115]
	v_mfma_f32_16x16x32_bf16 v[112:115], v[146:149], v[204:207], v[112:115]
	v_mfma_f32_16x16x32_bf16 v[96:99], v[146:149], v[212:215], v[96:99]
	v_mfma_f32_16x16x32_bf16 v[96:99], v[150:153], v[216:219], v[96:99]
	v_mfma_f32_16x16x32_bf16 v[92:95], v[176:179], v[216:219], v[92:95]
	v_mfma_f32_16x16x32_bf16 v[92:95], v[172:175], v[212:215], v[92:95]
	v_mfma_f32_16x16x32_bf16 v[76:79], v[172:175], v[228:231], v[76:79]
	v_mfma_f32_16x16x32_bf16 v[76:79], v[176:179], v[232:235], v[76:79]
	v_mfma_f32_16x16x32_bf16 v[80:83], v[150:153], v[232:235], v[80:83]
	v_mfma_f32_16x16x32_bf16 v[80:83], v[146:149], v[228:231], v[80:83]
	v_mfma_f32_16x16x32_bf16 v[120:123], v[180:183], v[196:199], v[120:123]
	v_mfma_f32_16x16x32_bf16 v[120:123], v[184:187], v[200:203], v[120:123]
	v_mfma_f32_16x16x32_bf16 v[116:119], v[192:195], v[200:203], v[116:119]
	v_mfma_f32_16x16x32_bf16 v[116:119], v[188:191], v[196:199], v[116:119]
	v_mfma_f32_16x16x32_bf16 v[100:103], v[188:191], v[204:207], v[100:103]
	v_mfma_f32_16x16x32_bf16 v[100:103], v[192:195], v[208:211], v[100:103]
	v_mfma_f32_16x16x32_bf16 v[104:107], v[184:187], v[208:211], v[104:107]
	v_mfma_f32_16x16x32_bf16 v[104:107], v[180:183], v[204:207], v[104:107]
	v_mfma_f32_16x16x32_bf16 v[88:91], v[180:183], v[212:215], v[88:91]
	v_mfma_f32_16x16x32_bf16 v[88:91], v[184:187], v[216:219], v[88:91]
	v_mfma_f32_16x16x32_bf16 v[84:87], v[192:195], v[216:219], v[84:87]
	v_mfma_f32_16x16x32_bf16 v[84:87], v[188:191], v[212:215], v[84:87]
	v_mfma_f32_16x16x32_bf16 v[68:71], v[188:191], v[228:231], v[68:71]
	v_mfma_f32_16x16x32_bf16 v[68:71], v[192:195], v[232:235], v[68:71]
	v_mfma_f32_16x16x32_bf16 v[72:75], v[184:187], v[232:235], v[72:75]
	v_mfma_f32_16x16x32_bf16 v[72:75], v[180:183], v[228:231], v[72:75]
	s_waitcnt vmcnt(8)
	s_setprio 0
	s_barrier
	s_add_u32 s54, s34, 0x160000
	s_addc_u32 s55, s35, 0
	s_add_i32 s52, s52, s19
	s_mov_b32 m0, s52
	ds_read_b128 v[196:199], v144 offset:49152
	ds_read_b128 v[200:203], v144 offset:50176
	ds_read_b128 v[204:207], v144 offset:51200
	ds_read_b128 v[208:211], v144 offset:52224
	ds_read_b128 v[212:215], v144 offset:53248
	ds_read_b128 v[216:219], v144 offset:54272
	ds_read_b128 v[228:231], v144 offset:55296
	ds_read_b128 v[232:235], v144 offset:56320
	global_load_lds_dwordx4 v134, s[54:55]
	s_add_i32 m0, s52, 0x2000
	s_add_u32 s34, s34, 0x164000
	s_addc_u32 s35, s35, 0
	s_add_i32 s52, s53, s19
	global_load_lds_dwordx4 v0, s[54:55]
	s_mov_b32 m0, s52
	s_nop 0
	global_load_lds_dwordx4 v134, s[34:35]
	s_add_i32 m0, s52, 0x2000
	s_nop 0
	global_load_lds_dwordx4 v0, s[34:35]
	s_mov_b32 m0, s61
	s_nop 0
	global_load_lds_dwordx4 v136, s[100:101]
	s_mov_b32 m0, s62
	s_nop 0
	global_load_lds_dwordx4 v132, s[100:101]
	s_waitcnt lgkmcnt(0)
	s_setprio 1
	v_mfma_f32_16x16x32_bf16 v[64:67], v[146:149], v[196:199], v[64:67]
	v_mfma_f32_16x16x32_bf16 v[64:67], v[150:153], v[200:203], v[64:67]
	v_mfma_f32_16x16x32_bf16 v[60:63], v[176:179], v[200:203], v[60:63]
	v_mfma_f32_16x16x32_bf16 v[60:63], v[172:175], v[196:199], v[60:63]
	v_mfma_f32_16x16x32_bf16 v[44:47], v[172:175], v[204:207], v[44:47]
	v_mfma_f32_16x16x32_bf16 v[44:47], v[176:179], v[208:211], v[44:47]
	v_mfma_f32_16x16x32_bf16 v[48:51], v[150:153], v[208:211], v[48:51]
	v_mfma_f32_16x16x32_bf16 v[48:51], v[146:149], v[204:207], v[48:51]
	v_mfma_f32_16x16x32_bf16 v[32:35], v[146:149], v[212:215], v[32:35]
	v_mfma_f32_16x16x32_bf16 v[32:35], v[150:153], v[216:219], v[32:35]
	v_mfma_f32_16x16x32_bf16 v[28:31], v[176:179], v[216:219], v[28:31]
	v_mfma_f32_16x16x32_bf16 v[28:31], v[172:175], v[212:215], v[28:31]
	v_mfma_f32_16x16x32_bf16 v[12:15], v[172:175], v[228:231], v[12:15]
	v_mfma_f32_16x16x32_bf16 v[12:15], v[176:179], v[232:235], v[12:15]
	v_mfma_f32_16x16x32_bf16 v[16:19], v[150:153], v[232:235], v[16:19]
	v_mfma_f32_16x16x32_bf16 v[16:19], v[146:149], v[228:231], v[16:19]
	v_mfma_f32_16x16x32_bf16 v[56:59], v[180:183], v[196:199], v[56:59]
	v_mfma_f32_16x16x32_bf16 v[56:59], v[184:187], v[200:203], v[56:59]
	v_mfma_f32_16x16x32_bf16 v[52:55], v[192:195], v[200:203], v[52:55]
	v_mfma_f32_16x16x32_bf16 v[52:55], v[188:191], v[196:199], v[52:55]
	v_mfma_f32_16x16x32_bf16 v[36:39], v[188:191], v[204:207], v[36:39]
	v_mfma_f32_16x16x32_bf16 v[36:39], v[192:195], v[208:211], v[36:39]
	v_mfma_f32_16x16x32_bf16 v[40:43], v[184:187], v[208:211], v[40:43]
	v_mfma_f32_16x16x32_bf16 v[40:43], v[180:183], v[204:207], v[40:43]
	v_mfma_f32_16x16x32_bf16 v[24:27], v[180:183], v[212:215], v[24:27]
	v_mfma_f32_16x16x32_bf16 v[24:27], v[184:187], v[216:219], v[24:27]
	v_mfma_f32_16x16x32_bf16 v[20:23], v[192:195], v[216:219], v[20:23]
	v_mfma_f32_16x16x32_bf16 v[20:23], v[188:191], v[212:215], v[20:23]
	v_mfma_f32_16x16x32_bf16 v[4:7], v[188:191], v[228:231], v[4:7]
	v_mfma_f32_16x16x32_bf16 v[4:7], v[192:195], v[232:235], v[4:7]
	v_mfma_f32_16x16x32_bf16 v[8:11], v[184:187], v[232:235], v[8:11]
	v_mfma_f32_16x16x32_bf16 v[8:11], v[180:183], v[228:231], v[8:11]
	s_waitcnt vmcnt(8)
	s_setprio 0
	s_barrier
	s_add_i32 s77, s77, 2
	s_add_u32 s71, s71, 0x2c0000
	s_addc_u32 s76, s76, 0
	s_add_u32 s50, s50, 0x100
	s_addc_u32 s51, s51, 0
	s_cmp_gt_u32 s77, 29
	s_cbranch_scc0 .LBB0_169
	s_branch .Lkdone_1
.Ltrail_1:
	s_add_u32 s34, s50, 0xfff80080
	s_addc_u32 s35, s51, -1
	s_add_i32 s52, 0, 0x10000
	s_cmp_eq_u32 s77, 28
	s_cselect_b32 s55, s36, s35
	s_cselect_b32 s54, s37, s34
	v_add_u32_e32 v145, s52, v142
	s_cselect_b32 s35, s41, s76
	s_cselect_b32 s34, s43, s71
	s_add_i32 s53, 0, 0x14000
	ds_read_b128 v[146:149], v145
	ds_read_b128 v[150:153], v145 offset:1024
	ds_read_b128 v[172:175], v145 offset:2048
	ds_read_b128 v[176:179], v145 offset:3072
	v_add_u32_e32 v145, s53, v142
	ds_read_b128 v[180:183], v145
	ds_read_b128 v[184:187], v145 offset:1024
	ds_read_b128 v[188:191], v145 offset:2048
	ds_read_b128 v[192:195], v145 offset:3072
	s_add_i32 m0, s57, 0xc000
	ds_read_b128 v[196:199], v144
	ds_read_b128 v[200:203], v144 offset:1024
	ds_read_b128 v[204:207], v144 offset:2048
	ds_read_b128 v[208:211], v144 offset:3072
	ds_read_b128 v[212:215], v144 offset:4096
	ds_read_b128 v[216:219], v144 offset:5120
	ds_read_b128 v[228:231], v144 offset:6144
	ds_read_b128 v[232:235], v144 offset:7168
	global_load_lds_dwordx4 v138, s[50:51]
	s_add_i32 m0, s57, 0xe000
	s_nop 0
	global_load_lds_dwordx4 v140, s[50:51]
	s_waitcnt vmcnt(8)
	s_waitcnt lgkmcnt(0)
	s_barrier
	s_setprio 2
	v_mfma_f32_16x16x32_bf16 v[128:131], v[146:149], v[196:199], v[128:131]
	v_mfma_f32_16x16x32_bf16 v[128:131], v[150:153], v[200:203], v[128:131]
	v_mfma_f32_16x16x32_bf16 v[124:127], v[176:179], v[200:203], v[124:127]
	v_mfma_f32_16x16x32_bf16 v[124:127], v[172:175], v[196:199], v[124:127]
	v_mfma_f32_16x16x32_bf16 v[108:111], v[172:175], v[204:207], v[108:111]
	v_mfma_f32_16x16x32_bf16 v[108:111], v[176:179], v[208:211], v[108:111]
	v_mfma_f32_16x16x32_bf16 v[112:115], v[150:153], v[208:211], v[112:115]
	v_mfma_f32_16x16x32_bf16 v[112:115], v[146:149], v[204:207], v[112:115]
	v_mfma_f32_16x16x32_bf16 v[96:99], v[146:149], v[212:215], v[96:99]
	v_mfma_f32_16x16x32_bf16 v[96:99], v[150:153], v[216:219], v[96:99]
	v_mfma_f32_16x16x32_bf16 v[92:95], v[176:179], v[216:219], v[92:95]
	v_mfma_f32_16x16x32_bf16 v[92:95], v[172:175], v[212:215], v[92:95]
	v_mfma_f32_16x16x32_bf16 v[76:79], v[172:175], v[228:231], v[76:79]
	v_mfma_f32_16x16x32_bf16 v[76:79], v[176:179], v[232:235], v[76:79]
	v_mfma_f32_16x16x32_bf16 v[80:83], v[150:153], v[232:235], v[80:83]
	v_mfma_f32_16x16x32_bf16 v[80:83], v[146:149], v[228:231], v[80:83]
	v_mfma_f32_16x16x32_bf16 v[120:123], v[180:183], v[196:199], v[120:123]
	v_mfma_f32_16x16x32_bf16 v[120:123], v[184:187], v[200:203], v[120:123]
	v_mfma_f32_16x16x32_bf16 v[116:119], v[192:195], v[200:203], v[116:119]
	v_mfma_f32_16x16x32_bf16 v[116:119], v[188:191], v[196:199], v[116:119]
	v_mfma_f32_16x16x32_bf16 v[100:103], v[188:191], v[204:207], v[100:103]
	v_mfma_f32_16x16x32_bf16 v[100:103], v[192:195], v[208:211], v[100:103]
	v_mfma_f32_16x16x32_bf16 v[104:107], v[184:187], v[208:211], v[104:107]
	v_mfma_f32_16x16x32_bf16 v[104:107], v[180:183], v[204:207], v[104:107]
	v_mfma_f32_16x16x32_bf16 v[88:91], v[180:183], v[212:215], v[88:91]
	v_mfma_f32_16x16x32_bf16 v[88:91], v[184:187], v[216:219], v[88:91]
	v_mfma_f32_16x16x32_bf16 v[84:87], v[192:195], v[216:219], v[84:87]
	v_mfma_f32_16x16x32_bf16 v[84:87], v[188:191], v[212:215], v[84:87]
	v_mfma_f32_16x16x32_bf16 v[68:71], v[188:191], v[228:231], v[68:71]
	v_mfma_f32_16x16x32_bf16 v[68:71], v[192:195], v[232:235], v[68:71]
	v_mfma_f32_16x16x32_bf16 v[72:75], v[184:187], v[232:235], v[72:75]
	v_mfma_f32_16x16x32_bf16 v[72:75], v[180:183], v[228:231], v[72:75]
	s_add_u32 s100, s54, s14
	s_addc_u32 s101, s55, s15
	s_add_i32 s52, s52, s19
	s_mov_b32 m0, s52
	ds_read_b128 v[196:199], v144 offset:16384
	ds_read_b128 v[200:203], v144 offset:17408
	ds_read_b128 v[204:207], v144 offset:18432
	ds_read_b128 v[208:211], v144 offset:19456
	ds_read_b128 v[212:215], v144 offset:20480
	ds_read_b128 v[216:219], v144 offset:21504
	ds_read_b128 v[228:231], v144 offset:22528
	ds_read_b128 v[232:235], v144 offset:23552
	global_load_lds_dwordx4 v134, s[34:35]
	s_add_i32 m0, s52, 0x2000
	s_add_u32 s96, s34, 0x4000
	s_addc_u32 s97, s35, 0
	s_add_i32 s52, s53, s19
	global_load_lds_dwordx4 v0, s[34:35]
	s_mov_b32 m0, s52
	s_nop 0
	global_load_lds_dwordx4 v134, s[96:97]
	s_add_i32 m0, s52, 0x2000
	s_nop 0
	global_load_lds_dwordx4 v0, s[96:97]
	s_mov_b32 m0, s57
	s_nop 0
	global_load_lds_dwordx4 v136, s[54:55]
	s_mov_b32 m0, s58
	s_nop 0
	global_load_lds_dwordx4 v132, s[54:55]
	s_waitcnt vmcnt(8)
	s_waitcnt lgkmcnt(0)
	s_barrier
	s_setprio 2
	v_mfma_f32_16x16x32_bf16 v[64:67], v[146:149], v[196:199], v[64:67]
	v_mfma_f32_16x16x32_bf16 v[64:67], v[150:153], v[200:203], v[64:67]
	v_mfma_f32_16x16x32_bf16 v[60:63], v[176:179], v[200:203], v[60:63]
	v_mfma_f32_16x16x32_bf16 v[60:63], v[172:175], v[196:199], v[60:63]
	v_mfma_f32_16x16x32_bf16 v[44:47], v[172:175], v[204:207], v[44:47]
	v_mfma_f32_16x16x32_bf16 v[44:47], v[176:179], v[208:211], v[44:47]
	v_mfma_f32_16x16x32_bf16 v[48:51], v[150:153], v[208:211], v[48:51]
	v_mfma_f32_16x16x32_bf16 v[48:51], v[146:149], v[204:207], v[48:51]
	v_mfma_f32_16x16x32_bf16 v[32:35], v[146:149], v[212:215], v[32:35]
	v_mfma_f32_16x16x32_bf16 v[32:35], v[150:153], v[216:219], v[32:35]
	v_mfma_f32_16x16x32_bf16 v[28:31], v[176:179], v[216:219], v[28:31]
	v_mfma_f32_16x16x32_bf16 v[28:31], v[172:175], v[212:215], v[28:31]
	v_mfma_f32_16x16x32_bf16 v[12:15], v[172:175], v[228:231], v[12:15]
	v_mfma_f32_16x16x32_bf16 v[12:15], v[176:179], v[232:235], v[12:15]
	v_mfma_f32_16x16x32_bf16 v[16:19], v[150:153], v[232:235], v[16:19]
	v_mfma_f32_16x16x32_bf16 v[16:19], v[146:149], v[228:231], v[16:19]
	v_mfma_f32_16x16x32_bf16 v[56:59], v[180:183], v[196:199], v[56:59]
	v_mfma_f32_16x16x32_bf16 v[56:59], v[184:187], v[200:203], v[56:59]
	v_mfma_f32_16x16x32_bf16 v[52:55], v[192:195], v[200:203], v[52:55]
	v_mfma_f32_16x16x32_bf16 v[52:55], v[188:191], v[196:199], v[52:55]
	v_mfma_f32_16x16x32_bf16 v[36:39], v[188:191], v[204:207], v[36:39]
	v_mfma_f32_16x16x32_bf16 v[36:39], v[192:195], v[208:211], v[36:39]
	v_mfma_f32_16x16x32_bf16 v[40:43], v[184:187], v[208:211], v[40:43]
	v_mfma_f32_16x16x32_bf16 v[40:43], v[180:183], v[204:207], v[40:43]
	v_mfma_f32_16x16x32_bf16 v[24:27], v[180:183], v[212:215], v[24:27]
	v_mfma_f32_16x16x32_bf16 v[24:27], v[184:187], v[216:219], v[24:27]
	v_mfma_f32_16x16x32_bf16 v[20:23], v[192:195], v[216:219], v[20:23]
	v_mfma_f32_16x16x32_bf16 v[20:23], v[188:191], v[212:215], v[20:23]
	v_mfma_f32_16x16x32_bf16 v[4:7], v[188:191], v[228:231], v[4:7]
	v_mfma_f32_16x16x32_bf16 v[4:7], v[192:195], v[232:235], v[4:7]
	v_mfma_f32_16x16x32_bf16 v[8:11], v[184:187], v[232:235], v[8:11]
	v_mfma_f32_16x16x32_bf16 v[8:11], v[180:183], v[228:231], v[8:11]
	s_add_i32 s52, 0, 0x18000
	v_add_u32_e32 v145, s52, v142
	s_add_i32 s53, 0, 0x1c000
	ds_read_b128 v[146:149], v145
	ds_read_b128 v[150:153], v145 offset:1024
	ds_read_b128 v[172:175], v145 offset:2048
	ds_read_b128 v[176:179], v145 offset:3072
	v_add_u32_e32 v145, s53, v142
	ds_read_b128 v[180:183], v145
	ds_read_b128 v[184:187], v145 offset:1024
	ds_read_b128 v[188:191], v145 offset:2048
	ds_read_b128 v[192:195], v145 offset:3072
	s_add_u32 s54, s54, 0x80000
	s_addc_u32 s55, s55, 0
	s_mov_b32 m0, s59
	ds_read_b128 v[196:199], v144 offset:32768
	ds_read_b128 v[200:203], v144 offset:33792
	ds_read_b128 v[204:207], v144 offset:34816
	ds_read_b128 v[208:211], v144 offset:35840
	ds_read_b128 v[212:215], v144 offset:36864
	ds_read_b128 v[216:219], v144 offset:37888
	ds_read_b128 v[228:231], v144 offset:38912
	ds_read_b128 v[232:235], v144 offset:39936
	global_load_lds_dwordx4 v136, s[54:55]
	s_mov_b32 m0, s60
	s_nop 0
	global_load_lds_dwordx4 v132, s[54:55]
	s_waitcnt vmcnt(8)
	s_waitcnt lgkmcnt(0)
	s_barrier
	s_setprio 2
	v_mfma_f32_16x16x32_bf16 v[128:131], v[146:149], v[196:199], v[128:131]
	v_mfma_f32_16x16x32_bf16 v[128:131], v[150:153], v[200:203], v[128:131]
	v_mfma_f32_16x16x32_bf16 v[124:127], v[176:179], v[200:203], v[124:127]
	v_mfma_f32_16x16x32_bf16 v[124:127], v[172:175], v[196:199], v[124:127]
	v_mfma_f32_16x16x32_bf16 v[108:111], v[172:175], v[204:207], v[108:111]
	v_mfma_f32_16x16x32_bf16 v[108:111], v[176:179], v[208:211], v[108:111]
	v_mfma_f32_16x16x32_bf16 v[112:115], v[150:153], v[208:211], v[112:115]
	v_mfma_f32_16x16x32_bf16 v[112:115], v[146:149], v[204:207], v[112:115]
	v_mfma_f32_16x16x32_bf16 v[96:99], v[146:149], v[212:215], v[96:99]
	v_mfma_f32_16x16x32_bf16 v[96:99], v[150:153], v[216:219], v[96:99]
	v_mfma_f32_16x16x32_bf16 v[92:95], v[176:179], v[216:219], v[92:95]
	v_mfma_f32_16x16x32_bf16 v[92:95], v[172:175], v[212:215], v[92:95]
	v_mfma_f32_16x16x32_bf16 v[76:79], v[172:175], v[228:231], v[76:79]
	v_mfma_f32_16x16x32_bf16 v[76:79], v[176:179], v[232:235], v[76:79]
	v_mfma_f32_16x16x32_bf16 v[80:83], v[150:153], v[232:235], v[80:83]
	v_mfma_f32_16x16x32_bf16 v[80:83], v[146:149], v[228:231], v[80:83]
	v_mfma_f32_16x16x32_bf16 v[120:123], v[180:183], v[196:199], v[120:123]
	v_mfma_f32_16x16x32_bf16 v[120:123], v[184:187], v[200:203], v[120:123]
	v_mfma_f32_16x16x32_bf16 v[116:119], v[192:195], v[200:203], v[116:119]
	v_mfma_f32_16x16x32_bf16 v[116:119], v[188:191], v[196:199], v[116:119]
	v_mfma_f32_16x16x32_bf16 v[100:103], v[188:191], v[204:207], v[100:103]
	v_mfma_f32_16x16x32_bf16 v[100:103], v[192:195], v[208:211], v[100:103]
	v_mfma_f32_16x16x32_bf16 v[104:107], v[184:187], v[208:211], v[104:107]
	v_mfma_f32_16x16x32_bf16 v[104:107], v[180:183], v[204:207], v[104:107]
	v_mfma_f32_16x16x32_bf16 v[88:91], v[180:183], v[212:215], v[88:91]
	v_mfma_f32_16x16x32_bf16 v[88:91], v[184:187], v[216:219], v[88:91]
	v_mfma_f32_16x16x32_bf16 v[84:87], v[192:195], v[216:219], v[84:87]
	v_mfma_f32_16x16x32_bf16 v[84:87], v[188:191], v[212:215], v[84:87]
	v_mfma_f32_16x16x32_bf16 v[68:71], v[188:191], v[228:231], v[68:71]
	v_mfma_f32_16x16x32_bf16 v[68:71], v[192:195], v[232:235], v[68:71]
	v_mfma_f32_16x16x32_bf16 v[72:75], v[184:187], v[232:235], v[72:75]
	v_mfma_f32_16x16x32_bf16 v[72:75], v[180:183], v[228:231], v[72:75]
	s_add_u32 s54, s34, 0x160000
	s_addc_u32 s55, s35, 0
	s_add_i32 s52, s52, s19
	s_mov_b32 m0, s52
	ds_read_b128 v[196:199], v144 offset:49152
	ds_read_b128 v[200:203], v144 offset:50176
	ds_read_b128 v[204:207], v144 offset:51200
	ds_read_b128 v[208:211], v144 offset:52224
	ds_read_b128 v[212:215], v144 offset:53248
	ds_read_b128 v[216:219], v144 offset:54272
	ds_read_b128 v[228:231], v144 offset:55296
	ds_read_b128 v[232:235], v144 offset:56320
	global_load_lds_dwordx4 v134, s[54:55]
	s_add_i32 m0, s52, 0x2000
	s_add_u32 s34, s34, 0x164000
	s_addc_u32 s35, s35, 0
	s_add_i32 s52, s53, s19
	global_load_lds_dwordx4 v0, s[54:55]
	s_mov_b32 m0, s52
	s_nop 0
	global_load_lds_dwordx4 v134, s[34:35]
	s_add_i32 m0, s52, 0x2000
	s_nop 0
	global_load_lds_dwordx4 v0, s[34:35]
	s_mov_b32 m0, s61
	s_nop 0
	global_load_lds_dwordx4 v136, s[100:101]
	s_mov_b32 m0, s62
	s_nop 0
	global_load_lds_dwordx4 v132, s[100:101]
	s_waitcnt vmcnt(8)
	s_waitcnt lgkmcnt(0)
	s_barrier
	s_setprio 2
	v_mfma_f32_16x16x32_bf16 v[64:67], v[146:149], v[196:199], v[64:67]
	v_mfma_f32_16x16x32_bf16 v[64:67], v[150:153], v[200:203], v[64:67]
	v_mfma_f32_16x16x32_bf16 v[60:63], v[176:179], v[200:203], v[60:63]
	v_mfma_f32_16x16x32_bf16 v[60:63], v[172:175], v[196:199], v[60:63]
	v_mfma_f32_16x16x32_bf16 v[44:47], v[172:175], v[204:207], v[44:47]
	v_mfma_f32_16x16x32_bf16 v[44:47], v[176:179], v[208:211], v[44:47]
	v_mfma_f32_16x16x32_bf16 v[48:51], v[150:153], v[208:211], v[48:51]
	v_mfma_f32_16x16x32_bf16 v[48:51], v[146:149], v[204:207], v[48:51]
	v_mfma_f32_16x16x32_bf16 v[32:35], v[146:149], v[212:215], v[32:35]
	v_mfma_f32_16x16x32_bf16 v[32:35], v[150:153], v[216:219], v[32:35]
	v_mfma_f32_16x16x32_bf16 v[28:31], v[176:179], v[216:219], v[28:31]
	v_mfma_f32_16x16x32_bf16 v[28:31], v[172:175], v[212:215], v[28:31]
	v_mfma_f32_16x16x32_bf16 v[12:15], v[172:175], v[228:231], v[12:15]
	v_mfma_f32_16x16x32_bf16 v[12:15], v[176:179], v[232:235], v[12:15]
	v_mfma_f32_16x16x32_bf16 v[16:19], v[150:153], v[232:235], v[16:19]
	v_mfma_f32_16x16x32_bf16 v[16:19], v[146:149], v[228:231], v[16:19]
	v_mfma_f32_16x16x32_bf16 v[56:59], v[180:183], v[196:199], v[56:59]
	v_mfma_f32_16x16x32_bf16 v[56:59], v[184:187], v[200:203], v[56:59]
	v_mfma_f32_16x16x32_bf16 v[52:55], v[192:195], v[200:203], v[52:55]
	v_mfma_f32_16x16x32_bf16 v[52:55], v[188:191], v[196:199], v[52:55]
	v_mfma_f32_16x16x32_bf16 v[36:39], v[188:191], v[204:207], v[36:39]
	v_mfma_f32_16x16x32_bf16 v[36:39], v[192:195], v[208:211], v[36:39]
	v_mfma_f32_16x16x32_bf16 v[40:43], v[184:187], v[208:211], v[40:43]
	v_mfma_f32_16x16x32_bf16 v[40:43], v[180:183], v[204:207], v[40:43]
	v_mfma_f32_16x16x32_bf16 v[24:27], v[180:183], v[212:215], v[24:27]
	v_mfma_f32_16x16x32_bf16 v[24:27], v[184:187], v[216:219], v[24:27]
	v_mfma_f32_16x16x32_bf16 v[20:23], v[192:195], v[216:219], v[20:23]
	v_mfma_f32_16x16x32_bf16 v[20:23], v[188:191], v[212:215], v[20:23]
	v_mfma_f32_16x16x32_bf16 v[4:7], v[188:191], v[228:231], v[4:7]
	v_mfma_f32_16x16x32_bf16 v[4:7], v[192:195], v[232:235], v[4:7]
	v_mfma_f32_16x16x32_bf16 v[8:11], v[184:187], v[232:235], v[8:11]
	v_mfma_f32_16x16x32_bf16 v[8:11], v[180:183], v[228:231], v[8:11]
	s_add_i32 s77, s77, 2
	s_add_u32 s71, s71, 0x2c0000
	s_addc_u32 s76, s76, 0
	s_add_u32 s50, s50, 0x100
	s_addc_u32 s51, s51, 0
	s_cmp_gt_u32 s77, 29
	s_cbranch_scc0 .Ltrail_1
.Lkdone_1:
	s_setprio 0
	s_and_b64 vcc, exec, s[28:29]
	s_nop 0
	s_barrier

.LBB0_243:
	s_add_u32 s34, s44, 0xfff80080
	s_addc_u32 s35, s45, -1
	s_add_i32 s52, 0, 0x10000
	s_cmp_eq_u32 vcc_hi, 28
	s_cselect_b32 s47, s36, s35
	s_cselect_b32 s46, s37, s34
	s_cselect_b32 s35, s55, vcc_lo
	s_cselect_b32 s34, s57, s63
	s_add_i32 s68, 0, 0x14000
	v_add_u32_e32 v144, s52, v155
	v_add_u32_e32 v180, s68, v155
	ds_read_b128 v[132:135], v144
	ds_read_b128 v[136:139], v144 offset:1024
	ds_read_b128 v[140:143], v144 offset:2048
	ds_read_b128 v[144:147], v144 offset:3072
	ds_read_b128 v[176:179], v180
	ds_read_b128 v[182:185], v180 offset:1024
	ds_read_b128 v[186:189], v180 offset:2048
	ds_read_b128 v[190:193], v180 offset:3072
	s_add_i32 m0, s69, 0xc000
	ds_read_b128 v[194:197], v181
	ds_read_b128 v[198:201], v181 offset:1024
	ds_read_b128 v[202:205], v181 offset:2048
	ds_read_b128 v[206:209], v181 offset:3072
	ds_read_b128 v[210:213], v181 offset:4096
	ds_read_b128 v[214:217], v181 offset:5120
	ds_read_b128 v[228:231], v181 offset:6144
	ds_read_b128 v[232:235], v181 offset:7168
	global_load_lds_dwordx4 v172, s[44:45]
	s_add_i32 m0, s69, 0xe000
	s_nop 0
	global_load_lds_dwordx4 v174, s[44:45]
	s_waitcnt lgkmcnt(0)
	s_setprio 1
	v_mfma_f32_16x16x32_bf16 v[128:131], v[132:135], v[194:197], v[128:131]
	v_mfma_f32_16x16x32_bf16 v[128:131], v[136:139], v[198:201], v[128:131]
	v_mfma_f32_16x16x32_bf16 v[124:127], v[144:147], v[198:201], v[124:127]
	v_mfma_f32_16x16x32_bf16 v[124:127], v[140:143], v[194:197], v[124:127]
	v_mfma_f32_16x16x32_bf16 v[108:111], v[140:143], v[202:205], v[108:111]
	v_mfma_f32_16x16x32_bf16 v[108:111], v[144:147], v[206:209], v[108:111]
	v_mfma_f32_16x16x32_bf16 v[112:115], v[136:139], v[206:209], v[112:115]
	v_mfma_f32_16x16x32_bf16 v[112:115], v[132:135], v[202:205], v[112:115]
	v_mfma_f32_16x16x32_bf16 v[96:99], v[132:135], v[210:213], v[96:99]
	v_mfma_f32_16x16x32_bf16 v[96:99], v[136:139], v[214:217], v[96:99]
	v_mfma_f32_16x16x32_bf16 v[92:95], v[144:147], v[214:217], v[92:95]
	v_mfma_f32_16x16x32_bf16 v[92:95], v[140:143], v[210:213], v[92:95]
	v_mfma_f32_16x16x32_bf16 v[76:79], v[140:143], v[228:231], v[76:79]
	v_mfma_f32_16x16x32_bf16 v[76:79], v[144:147], v[232:235], v[76:79]
	v_mfma_f32_16x16x32_bf16 v[80:83], v[136:139], v[232:235], v[80:83]
	v_mfma_f32_16x16x32_bf16 v[80:83], v[132:135], v[228:231], v[80:83]
	v_mfma_f32_16x16x32_bf16 v[120:123], v[176:179], v[194:197], v[120:123]
	v_mfma_f32_16x16x32_bf16 v[120:123], v[182:185], v[198:201], v[120:123]
	v_mfma_f32_16x16x32_bf16 v[116:119], v[190:193], v[198:201], v[116:119]
	v_mfma_f32_16x16x32_bf16 v[116:119], v[186:189], v[194:197], v[116:119]
	v_mfma_f32_16x16x32_bf16 v[100:103], v[186:189], v[202:205], v[100:103]
	v_mfma_f32_16x16x32_bf16 v[100:103], v[190:193], v[206:209], v[100:103]
	v_mfma_f32_16x16x32_bf16 v[104:107], v[182:185], v[206:209], v[104:107]
	v_mfma_f32_16x16x32_bf16 v[104:107], v[176:179], v[202:205], v[104:107]
	v_mfma_f32_16x16x32_bf16 v[88:91], v[176:179], v[210:213], v[88:91]
	v_mfma_f32_16x16x32_bf16 v[88:91], v[182:185], v[214:217], v[88:91]
	v_mfma_f32_16x16x32_bf16 v[84:87], v[190:193], v[214:217], v[84:87]
	v_mfma_f32_16x16x32_bf16 v[84:87], v[186:189], v[210:213], v[84:87]
	v_mfma_f32_16x16x32_bf16 v[68:71], v[186:189], v[228:231], v[68:71]
	v_mfma_f32_16x16x32_bf16 v[68:71], v[190:193], v[232:235], v[68:71]
	v_mfma_f32_16x16x32_bf16 v[72:75], v[182:185], v[232:235], v[72:75]
	v_mfma_f32_16x16x32_bf16 v[72:75], v[176:179], v[228:231], v[72:75]
	s_waitcnt vmcnt(8)
	s_setprio 0
	s_barrier
	s_add_u32 s100, s46, s14
	s_addc_u32 s101, s47, s15
	s_add_i32 s52, s52, s2
	s_mov_b32 m0, s52
	ds_read_b128 v[194:197], v181 offset:16384
	ds_read_b128 v[198:201], v181 offset:17408
	ds_read_b128 v[202:205], v181 offset:18432
	ds_read_b128 v[206:209], v181 offset:19456
	ds_read_b128 v[210:213], v181 offset:20480
	ds_read_b128 v[214:217], v181 offset:21504
	ds_read_b128 v[228:231], v181 offset:22528
	ds_read_b128 v[232:235], v181 offset:23552
	global_load_lds_dwordx4 v150, s[34:35]
	s_add_i32 m0, s52, 0x2000
	s_add_u32 s52, s34, 0x4000
	s_addc_u32 s53, s35, 0
	s_add_i32 s68, s68, s2
	global_load_lds_dwordx4 v0, s[34:35]
	s_mov_b32 m0, s68
	s_nop 0
	global_load_lds_dwordx4 v150, s[52:53]
	s_add_i32 m0, s68, 0x2000
	s_nop 0
	global_load_lds_dwordx4 v0, s[52:53]
	s_mov_b32 m0, s69
	s_nop 0
	global_load_lds_dwordx4 v152, s[46:47]
	s_mov_b32 m0, s71
	s_nop 0
	global_load_lds_dwordx4 v148, s[46:47]
	s_waitcnt lgkmcnt(0)
	s_setprio 1
	v_mfma_f32_16x16x32_bf16 v[64:67], v[132:135], v[194:197], v[64:67]
	v_mfma_f32_16x16x32_bf16 v[64:67], v[136:139], v[198:201], v[64:67]
	v_mfma_f32_16x16x32_bf16 v[60:63], v[144:147], v[198:201], v[60:63]
	v_mfma_f32_16x16x32_bf16 v[60:63], v[140:143], v[194:197], v[60:63]
	v_mfma_f32_16x16x32_bf16 v[44:47], v[140:143], v[202:205], v[44:47]
	v_mfma_f32_16x16x32_bf16 v[44:47], v[144:147], v[206:209], v[44:47]
	v_mfma_f32_16x16x32_bf16 v[48:51], v[136:139], v[206:209], v[48:51]
	v_mfma_f32_16x16x32_bf16 v[48:51], v[132:135], v[202:205], v[48:51]
	v_mfma_f32_16x16x32_bf16 v[32:35], v[132:135], v[210:213], v[32:35]
	v_mfma_f32_16x16x32_bf16 v[32:35], v[136:139], v[214:217], v[32:35]
	v_mfma_f32_16x16x32_bf16 v[28:31], v[144:147], v[214:217], v[28:31]
	v_mfma_f32_16x16x32_bf16 v[28:31], v[140:143], v[210:213], v[28:31]
	v_mfma_f32_16x16x32_bf16 v[12:15], v[140:143], v[228:231], v[12:15]
	v_mfma_f32_16x16x32_bf16 v[12:15], v[144:147], v[232:235], v[12:15]
	v_mfma_f32_16x16x32_bf16 v[16:19], v[136:139], v[232:235], v[16:19]
	v_mfma_f32_16x16x32_bf16 v[16:19], v[132:135], v[228:231], v[16:19]
	v_mfma_f32_16x16x32_bf16 v[56:59], v[176:179], v[194:197], v[56:59]
	v_mfma_f32_16x16x32_bf16 v[56:59], v[182:185], v[198:201], v[56:59]
	v_mfma_f32_16x16x32_bf16 v[52:55], v[190:193], v[198:201], v[52:55]
	v_mfma_f32_16x16x32_bf16 v[52:55], v[186:189], v[194:197], v[52:55]
	v_mfma_f32_16x16x32_bf16 v[36:39], v[186:189], v[202:205], v[36:39]
	v_mfma_f32_16x16x32_bf16 v[36:39], v[190:193], v[206:209], v[36:39]
	v_mfma_f32_16x16x32_bf16 v[40:43], v[182:185], v[206:209], v[40:43]
	v_mfma_f32_16x16x32_bf16 v[40:43], v[176:179], v[202:205], v[40:43]
	v_mfma_f32_16x16x32_bf16 v[24:27], v[176:179], v[210:213], v[24:27]
	v_mfma_f32_16x16x32_bf16 v[24:27], v[182:185], v[214:217], v[24:27]
	v_mfma_f32_16x16x32_bf16 v[20:23], v[190:193], v[214:217], v[20:23]
	v_mfma_f32_16x16x32_bf16 v[20:23], v[186:189], v[210:213], v[20:23]
	v_mfma_f32_16x16x32_bf16 v[4:7], v[186:189], v[228:231], v[4:7]
	v_mfma_f32_16x16x32_bf16 v[4:7], v[190:193], v[232:235], v[4:7]
	v_mfma_f32_16x16x32_bf16 v[8:11], v[182:185], v[232:235], v[8:11]
	v_mfma_f32_16x16x32_bf16 v[8:11], v[176:179], v[228:231], v[8:11]
	s_waitcnt vmcnt(8)
	s_setprio 0
	s_barrier
	s_add_i32 s52, 0, 0x18000
	s_add_i32 s53, 0, 0x1c000
	v_add_u32_e32 v144, s52, v155
	v_add_u32_e32 v180, s53, v155
	ds_read_b128 v[132:135], v144
	ds_read_b128 v[136:139], v144 offset:1024
	ds_read_b128 v[140:143], v144 offset:2048
	ds_read_b128 v[144:147], v144 offset:3072
	ds_read_b128 v[176:179], v180
	ds_read_b128 v[182:185], v180 offset:1024
	ds_read_b128 v[186:189], v180 offset:2048
	ds_read_b128 v[190:193], v180 offset:3072
	s_add_u32 s46, s46, 0x80000
	s_addc_u32 s47, s47, 0
	s_mov_b32 m0, s88
	ds_read_b128 v[194:197], v181 offset:32768
	ds_read_b128 v[198:201], v181 offset:33792
	ds_read_b128 v[202:205], v181 offset:34816
	ds_read_b128 v[206:209], v181 offset:35840
	ds_read_b128 v[210:213], v181 offset:36864
	ds_read_b128 v[214:217], v181 offset:37888
	ds_read_b128 v[228:231], v181 offset:38912
	ds_read_b128 v[232:235], v181 offset:39936
	global_load_lds_dwordx4 v152, s[46:47]
	s_mov_b32 m0, s96
	s_nop 0
	global_load_lds_dwordx4 v148, s[46:47]
	s_waitcnt lgkmcnt(0)
	s_setprio 1
	v_mfma_f32_16x16x32_bf16 v[128:131], v[132:135], v[194:197], v[128:131]
	v_mfma_f32_16x16x32_bf16 v[128:131], v[136:139], v[198:201], v[128:131]
	v_mfma_f32_16x16x32_bf16 v[124:127], v[144:147], v[198:201], v[124:127]
	v_mfma_f32_16x16x32_bf16 v[124:127], v[140:143], v[194:197], v[124:127]
	v_mfma_f32_16x16x32_bf16 v[108:111], v[140:143], v[202:205], v[108:111]
	v_mfma_f32_16x16x32_bf16 v[108:111], v[144:147], v[206:209], v[108:111]
	v_mfma_f32_16x16x32_bf16 v[112:115], v[136:139], v[206:209], v[112:115]
	v_mfma_f32_16x16x32_bf16 v[112:115], v[132:135], v[202:205], v[112:115]
	v_mfma_f32_16x16x32_bf16 v[96:99], v[132:135], v[210:213], v[96:99]
	v_mfma_f32_16x16x32_bf16 v[96:99], v[136:139], v[214:217], v[96:99]
	v_mfma_f32_16x16x32_bf16 v[92:95], v[144:147], v[214:217], v[92:95]
	v_mfma_f32_16x16x32_bf16 v[92:95], v[140:143], v[210:213], v[92:95]
	v_mfma_f32_16x16x32_bf16 v[76:79], v[140:143], v[228:231], v[76:79]
	v_mfma_f32_16x16x32_bf16 v[76:79], v[144:147], v[232:235], v[76:79]
	v_mfma_f32_16x16x32_bf16 v[80:83], v[136:139], v[232:235], v[80:83]
	v_mfma_f32_16x16x32_bf16 v[80:83], v[132:135], v[228:231], v[80:83]
	v_mfma_f32_16x16x32_bf16 v[120:123], v[176:179], v[194:197], v[120:123]
	v_mfma_f32_16x16x32_bf16 v[120:123], v[182:185], v[198:201], v[120:123]
	v_mfma_f32_16x16x32_bf16 v[116:119], v[190:193], v[198:201], v[116:119]
	v_mfma_f32_16x16x32_bf16 v[116:119], v[186:189], v[194:197], v[116:119]
	v_mfma_f32_16x16x32_bf16 v[100:103], v[186:189], v[202:205], v[100:103]
	v_mfma_f32_16x16x32_bf16 v[100:103], v[190:193], v[206:209], v[100:103]
	v_mfma_f32_16x16x32_bf16 v[104:107], v[182:185], v[206:209], v[104:107]
	v_mfma_f32_16x16x32_bf16 v[104:107], v[176:179], v[202:205], v[104:107]
	v_mfma_f32_16x16x32_bf16 v[88:91], v[176:179], v[210:213], v[88:91]
	v_mfma_f32_16x16x32_bf16 v[88:91], v[182:185], v[214:217], v[88:91]
	v_mfma_f32_16x16x32_bf16 v[84:87], v[190:193], v[214:217], v[84:87]
	v_mfma_f32_16x16x32_bf16 v[84:87], v[186:189], v[210:213], v[84:87]
	v_mfma_f32_16x16x32_bf16 v[68:71], v[186:189], v[228:231], v[68:71]
	v_mfma_f32_16x16x32_bf16 v[68:71], v[190:193], v[232:235], v[68:71]
	v_mfma_f32_16x16x32_bf16 v[72:75], v[182:185], v[232:235], v[72:75]
	v_mfma_f32_16x16x32_bf16 v[72:75], v[176:179], v[228:231], v[72:75]
	s_waitcnt vmcnt(8)
	s_setprio 0
	s_barrier
	s_add_u32 s46, s34, 0x70000
	s_addc_u32 s47, s35, 0
	s_add_i32 s52, s52, s2
	s_mov_b32 m0, s52
	ds_read_b128 v[194:197], v181 offset:49152
	ds_read_b128 v[198:201], v181 offset:50176
	ds_read_b128 v[202:205], v181 offset:51200
	ds_read_b128 v[206:209], v181 offset:52224
	ds_read_b128 v[210:213], v181 offset:53248
	ds_read_b128 v[214:217], v181 offset:54272
	ds_read_b128 v[228:231], v181 offset:55296
	ds_read_b128 v[232:235], v181 offset:56320
	global_load_lds_dwordx4 v150, s[46:47]
	s_add_i32 m0, s52, 0x2000
	s_add_u32 s34, s34, 0x74000
	global_load_lds_dwordx4 v0, s[46:47]
	s_addc_u32 s35, s35, 0
	s_add_i32 s46, s53, s2
	s_mov_b32 m0, s46
	s_nop 0
	global_load_lds_dwordx4 v150, s[34:35]
	s_add_i32 m0, s46, 0x2000
	s_nop 0
	global_load_lds_dwordx4 v0, s[34:35]
	s_mov_b32 m0, s97
	s_nop 0
	global_load_lds_dwordx4 v152, s[100:101]
	s_mov_b32 m0, s76
	s_nop 0
	global_load_lds_dwordx4 v148, s[100:101]
	s_waitcnt lgkmcnt(0)
	s_setprio 1
	v_mfma_f32_16x16x32_bf16 v[64:67], v[132:135], v[194:197], v[64:67]
	v_mfma_f32_16x16x32_bf16 v[64:67], v[136:139], v[198:201], v[64:67]
	v_mfma_f32_16x16x32_bf16 v[60:63], v[144:147], v[198:201], v[60:63]
	v_mfma_f32_16x16x32_bf16 v[60:63], v[140:143], v[194:197], v[60:63]
	v_mfma_f32_16x16x32_bf16 v[44:47], v[140:143], v[202:205], v[44:47]
	v_mfma_f32_16x16x32_bf16 v[44:47], v[144:147], v[206:209], v[44:47]
	v_mfma_f32_16x16x32_bf16 v[48:51], v[136:139], v[206:209], v[48:51]
	v_mfma_f32_16x16x32_bf16 v[48:51], v[132:135], v[202:205], v[48:51]
	v_mfma_f32_16x16x32_bf16 v[32:35], v[132:135], v[210:213], v[32:35]
	v_mfma_f32_16x16x32_bf16 v[32:35], v[136:139], v[214:217], v[32:35]
	v_mfma_f32_16x16x32_bf16 v[28:31], v[144:147], v[214:217], v[28:31]
	v_mfma_f32_16x16x32_bf16 v[28:31], v[140:143], v[210:213], v[28:31]
	v_mfma_f32_16x16x32_bf16 v[12:15], v[140:143], v[228:231], v[12:15]
	v_mfma_f32_16x16x32_bf16 v[12:15], v[144:147], v[232:235], v[12:15]
	v_mfma_f32_16x16x32_bf16 v[16:19], v[136:139], v[232:235], v[16:19]
	v_mfma_f32_16x16x32_bf16 v[16:19], v[132:135], v[228:231], v[16:19]
	v_mfma_f32_16x16x32_bf16 v[56:59], v[176:179], v[194:197], v[56:59]
	v_mfma_f32_16x16x32_bf16 v[56:59], v[182:185], v[198:201], v[56:59]
	v_mfma_f32_16x16x32_bf16 v[52:55], v[190:193], v[198:201], v[52:55]
	v_mfma_f32_16x16x32_bf16 v[52:55], v[186:189], v[194:197], v[52:55]
	v_mfma_f32_16x16x32_bf16 v[36:39], v[186:189], v[202:205], v[36:39]
	v_mfma_f32_16x16x32_bf16 v[36:39], v[190:193], v[206:209], v[36:39]
	v_mfma_f32_16x16x32_bf16 v[40:43], v[182:185], v[206:209], v[40:43]
	v_mfma_f32_16x16x32_bf16 v[40:43], v[176:179], v[202:205], v[40:43]
	v_mfma_f32_16x16x32_bf16 v[24:27], v[176:179], v[210:213], v[24:27]
	v_mfma_f32_16x16x32_bf16 v[24:27], v[182:185], v[214:217], v[24:27]
	v_mfma_f32_16x16x32_bf16 v[20:23], v[190:193], v[214:217], v[20:23]
	v_mfma_f32_16x16x32_bf16 v[20:23], v[186:189], v[210:213], v[20:23]
	v_mfma_f32_16x16x32_bf16 v[4:7], v[186:189], v[228:231], v[4:7]
	v_mfma_f32_16x16x32_bf16 v[4:7], v[190:193], v[232:235], v[4:7]
	v_mfma_f32_16x16x32_bf16 v[8:11], v[182:185], v[232:235], v[8:11]
	v_mfma_f32_16x16x32_bf16 v[8:11], v[176:179], v[228:231], v[8:11]
	s_waitcnt vmcnt(8)
	s_setprio 0
	s_barrier
	s_add_i32 vcc_hi, vcc_hi, 2
	s_add_u32 s63, s63, 0xe0000
	s_addc_u32 vcc_lo, vcc_lo, 0
	s_add_u32 s44, s44, 0x100
	s_addc_u32 s45, s45, 0
	s_cmp_gt_u32 vcc_hi, 29
	s_cbranch_scc0 .LBB0_243
	s_branch .Lkdone_2
.Ltrail_2:
	s_add_u32 s34, s44, 0xfff80080
	s_addc_u32 s35, s45, -1
	s_add_i32 s52, 0, 0x10000
	s_cmp_eq_u32 vcc_hi, 28
	s_cselect_b32 s47, s36, s35
	s_cselect_b32 s46, s37, s34
	s_cselect_b32 s35, s55, vcc_lo
	s_cselect_b32 s34, s57, s63
	s_add_i32 s68, 0, 0x14000
	v_add_u32_e32 v144, s52, v155
	v_add_u32_e32 v180, s68, v155
	ds_read_b128 v[132:135], v144
	ds_read_b128 v[136:139], v144 offset:1024
	ds_read_b128 v[140:143], v144 offset:2048
	ds_read_b128 v[144:147], v144 offset:3072
	ds_read_b128 v[176:179], v180
	ds_read_b128 v[182:185], v180 offset:1024
	ds_read_b128 v[186:189], v180 offset:2048
	ds_read_b128 v[190:193], v180 offset:3072
	s_add_i32 m0, s69, 0xc000
	ds_read_b128 v[194:197], v181
	ds_read_b128 v[198:201], v181 offset:1024
	ds_read_b128 v[202:205], v181 offset:2048
	ds_read_b128 v[206:209], v181 offset:3072
	ds_read_b128 v[210:213], v181 offset:4096
	ds_read_b128 v[214:217], v181 offset:5120
	ds_read_b128 v[228:231], v181 offset:6144
	ds_read_b128 v[232:235], v181 offset:7168
	global_load_lds_dwordx4 v172, s[44:45]
	s_add_i32 m0, s69, 0xe000
	s_nop 0
	global_load_lds_dwordx4 v174, s[44:45]
	s_waitcnt vmcnt(8)
	s_waitcnt lgkmcnt(0)
	s_barrier
	s_setprio 2
	v_mfma_f32_16x16x32_bf16 v[128:131], v[132:135], v[194:197], v[128:131]
	v_mfma_f32_16x16x32_bf16 v[128:131], v[136:139], v[198:201], v[128:131]
	v_mfma_f32_16x16x32_bf16 v[124:127], v[144:147], v[198:201], v[124:127]
	v_mfma_f32_16x16x32_bf16 v[124:127], v[140:143], v[194:197], v[124:127]
	v_mfma_f32_16x16x32_bf16 v[108:111], v[140:143], v[202:205], v[108:111]
	v_mfma_f32_16x16x32_bf16 v[108:111], v[144:147], v[206:209], v[108:111]
	v_mfma_f32_16x16x32_bf16 v[112:115], v[136:139], v[206:209], v[112:115]
	v_mfma_f32_16x16x32_bf16 v[112:115], v[132:135], v[202:205], v[112:115]
	v_mfma_f32_16x16x32_bf16 v[96:99], v[132:135], v[210:213], v[96:99]
	v_mfma_f32_16x16x32_bf16 v[96:99], v[136:139], v[214:217], v[96:99]
	v_mfma_f32_16x16x32_bf16 v[92:95], v[144:147], v[214:217], v[92:95]
	v_mfma_f32_16x16x32_bf16 v[92:95], v[140:143], v[210:213], v[92:95]
	v_mfma_f32_16x16x32_bf16 v[76:79], v[140:143], v[228:231], v[76:79]
	v_mfma_f32_16x16x32_bf16 v[76:79], v[144:147], v[232:235], v[76:79]
	v_mfma_f32_16x16x32_bf16 v[80:83], v[136:139], v[232:235], v[80:83]
	v_mfma_f32_16x16x32_bf16 v[80:83], v[132:135], v[228:231], v[80:83]
	v_mfma_f32_16x16x32_bf16 v[120:123], v[176:179], v[194:197], v[120:123]
	v_mfma_f32_16x16x32_bf16 v[120:123], v[182:185], v[198:201], v[120:123]
	v_mfma_f32_16x16x32_bf16 v[116:119], v[190:193], v[198:201], v[116:119]
	v_mfma_f32_16x16x32_bf16 v[116:119], v[186:189], v[194:197], v[116:119]
	v_mfma_f32_16x16x32_bf16 v[100:103], v[186:189], v[202:205], v[100:103]
	v_mfma_f32_16x16x32_bf16 v[100:103], v[190:193], v[206:209], v[100:103]
	v_mfma_f32_16x16x32_bf16 v[104:107], v[182:185], v[206:209], v[104:107]
	v_mfma_f32_16x16x32_bf16 v[104:107], v[176:179], v[202:205], v[104:107]
	v_mfma_f32_16x16x32_bf16 v[88:91], v[176:179], v[210:213], v[88:91]
	v_mfma_f32_16x16x32_bf16 v[88:91], v[182:185], v[214:217], v[88:91]
	v_mfma_f32_16x16x32_bf16 v[84:87], v[190:193], v[214:217], v[84:87]
	v_mfma_f32_16x16x32_bf16 v[84:87], v[186:189], v[210:213], v[84:87]
	v_mfma_f32_16x16x32_bf16 v[68:71], v[186:189], v[228:231], v[68:71]
	v_mfma_f32_16x16x32_bf16 v[68:71], v[190:193], v[232:235], v[68:71]
	v_mfma_f32_16x16x32_bf16 v[72:75], v[182:185], v[232:235], v[72:75]
	v_mfma_f32_16x16x32_bf16 v[72:75], v[176:179], v[228:231], v[72:75]
	s_add_u32 s100, s46, s14
	s_addc_u32 s101, s47, s15
	s_add_i32 s52, s52, s2
	s_mov_b32 m0, s52
	ds_read_b128 v[194:197], v181 offset:16384
	ds_read_b128 v[198:201], v181 offset:17408
	ds_read_b128 v[202:205], v181 offset:18432
	ds_read_b128 v[206:209], v181 offset:19456
	ds_read_b128 v[210:213], v181 offset:20480
	ds_read_b128 v[214:217], v181 offset:21504
	ds_read_b128 v[228:231], v181 offset:22528
	ds_read_b128 v[232:235], v181 offset:23552
	global_load_lds_dwordx4 v150, s[34:35]
	s_add_i32 m0, s52, 0x2000
	s_add_u32 s52, s34, 0x4000
	s_addc_u32 s53, s35, 0
	s_add_i32 s68, s68, s2
	global_load_lds_dwordx4 v0, s[34:35]
	s_mov_b32 m0, s68
	s_nop 0
	global_load_lds_dwordx4 v150, s[52:53]
	s_add_i32 m0, s68, 0x2000
	s_nop 0
	global_load_lds_dwordx4 v0, s[52:53]
	s_mov_b32 m0, s69
	s_nop 0
	global_load_lds_dwordx4 v152, s[46:47]
	s_mov_b32 m0, s71
	s_nop 0
	global_load_lds_dwordx4 v148, s[46:47]
	s_waitcnt vmcnt(8)
	s_waitcnt lgkmcnt(0)
	s_barrier
	s_setprio 2
	v_mfma_f32_16x16x32_bf16 v[64:67], v[132:135], v[194:197], v[64:67]
	v_mfma_f32_16x16x32_bf16 v[64:67], v[136:139], v[198:201], v[64:67]
	v_mfma_f32_16x16x32_bf16 v[60:63], v[144:147], v[198:201], v[60:63]
	v_mfma_f32_16x16x32_bf16 v[60:63], v[140:143], v[194:197], v[60:63]
	v_mfma_f32_16x16x32_bf16 v[44:47], v[140:143], v[202:205], v[44:47]
	v_mfma_f32_16x16x32_bf16 v[44:47], v[144:147], v[206:209], v[44:47]
	v_mfma_f32_16x16x32_bf16 v[48:51], v[136:139], v[206:209], v[48:51]
	v_mfma_f32_16x16x32_bf16 v[48:51], v[132:135], v[202:205], v[48:51]
	v_mfma_f32_16x16x32_bf16 v[32:35], v[132:135], v[210:213], v[32:35]
	v_mfma_f32_16x16x32_bf16 v[32:35], v[136:139], v[214:217], v[32:35]
	v_mfma_f32_16x16x32_bf16 v[28:31], v[144:147], v[214:217], v[28:31]
	v_mfma_f32_16x16x32_bf16 v[28:31], v[140:143], v[210:213], v[28:31]
	v_mfma_f32_16x16x32_bf16 v[12:15], v[140:143], v[228:231], v[12:15]
	v_mfma_f32_16x16x32_bf16 v[12:15], v[144:147], v[232:235], v[12:15]
	v_mfma_f32_16x16x32_bf16 v[16:19], v[136:139], v[232:235], v[16:19]
	v_mfma_f32_16x16x32_bf16 v[16:19], v[132:135], v[228:231], v[16:19]
	v_mfma_f32_16x16x32_bf16 v[56:59], v[176:179], v[194:197], v[56:59]
	v_mfma_f32_16x16x32_bf16 v[56:59], v[182:185], v[198:201], v[56:59]
	v_mfma_f32_16x16x32_bf16 v[52:55], v[190:193], v[198:201], v[52:55]
	v_mfma_f32_16x16x32_bf16 v[52:55], v[186:189], v[194:197], v[52:55]
	v_mfma_f32_16x16x32_bf16 v[36:39], v[186:189], v[202:205], v[36:39]
	v_mfma_f32_16x16x32_bf16 v[36:39], v[190:193], v[206:209], v[36:39]
	v_mfma_f32_16x16x32_bf16 v[40:43], v[182:185], v[206:209], v[40:43]
	v_mfma_f32_16x16x32_bf16 v[40:43], v[176:179], v[202:205], v[40:43]
	v_mfma_f32_16x16x32_bf16 v[24:27], v[176:179], v[210:213], v[24:27]
	v_mfma_f32_16x16x32_bf16 v[24:27], v[182:185], v[214:217], v[24:27]
	v_mfma_f32_16x16x32_bf16 v[20:23], v[190:193], v[214:217], v[20:23]
	v_mfma_f32_16x16x32_bf16 v[20:23], v[186:189], v[210:213], v[20:23]
	v_mfma_f32_16x16x32_bf16 v[4:7], v[186:189], v[228:231], v[4:7]
	v_mfma_f32_16x16x32_bf16 v[4:7], v[190:193], v[232:235], v[4:7]
	v_mfma_f32_16x16x32_bf16 v[8:11], v[182:185], v[232:235], v[8:11]
	v_mfma_f32_16x16x32_bf16 v[8:11], v[176:179], v[228:231], v[8:11]
	s_add_i32 s52, 0, 0x18000
	s_add_i32 s53, 0, 0x1c000
	v_add_u32_e32 v144, s52, v155
	v_add_u32_e32 v180, s53, v155
	ds_read_b128 v[132:135], v144
	ds_read_b128 v[136:139], v144 offset:1024
	ds_read_b128 v[140:143], v144 offset:2048
	ds_read_b128 v[144:147], v144 offset:3072
	ds_read_b128 v[176:179], v180
	ds_read_b128 v[182:185], v180 offset:1024
	ds_read_b128 v[186:189], v180 offset:2048
	ds_read_b128 v[190:193], v180 offset:3072
	s_add_u32 s46, s46, 0x80000
	s_addc_u32 s47, s47, 0
	s_mov_b32 m0, s88
	ds_read_b128 v[194:197], v181 offset:32768
	ds_read_b128 v[198:201], v181 offset:33792
	ds_read_b128 v[202:205], v181 offset:34816
	ds_read_b128 v[206:209], v181 offset:35840
	ds_read_b128 v[210:213], v181 offset:36864
	ds_read_b128 v[214:217], v181 offset:37888
	ds_read_b128 v[228:231], v181 offset:38912
	ds_read_b128 v[232:235], v181 offset:39936
	global_load_lds_dwordx4 v152, s[46:47]
	s_mov_b32 m0, s96
	s_nop 0
	global_load_lds_dwordx4 v148, s[46:47]
	s_waitcnt vmcnt(8)
	s_waitcnt lgkmcnt(0)
	s_barrier
	s_setprio 2
	v_mfma_f32_16x16x32_bf16 v[128:131], v[132:135], v[194:197], v[128:131]
	v_mfma_f32_16x16x32_bf16 v[128:131], v[136:139], v[198:201], v[128:131]
	v_mfma_f32_16x16x32_bf16 v[124:127], v[144:147], v[198:201], v[124:127]
	v_mfma_f32_16x16x32_bf16 v[124:127], v[140:143], v[194:197], v[124:127]
	v_mfma_f32_16x16x32_bf16 v[108:111], v[140:143], v[202:205], v[108:111]
	v_mfma_f32_16x16x32_bf16 v[108:111], v[144:147], v[206:209], v[108:111]
	v_mfma_f32_16x16x32_bf16 v[112:115], v[136:139], v[206:209], v[112:115]
	v_mfma_f32_16x16x32_bf16 v[112:115], v[132:135], v[202:205], v[112:115]
	v_mfma_f32_16x16x32_bf16 v[96:99], v[132:135], v[210:213], v[96:99]
	v_mfma_f32_16x16x32_bf16 v[96:99], v[136:139], v[214:217], v[96:99]
	v_mfma_f32_16x16x32_bf16 v[92:95], v[144:147], v[214:217], v[92:95]
	v_mfma_f32_16x16x32_bf16 v[92:95], v[140:143], v[210:213], v[92:95]
	v_mfma_f32_16x16x32_bf16 v[76:79], v[140:143], v[228:231], v[76:79]
	v_mfma_f32_16x16x32_bf16 v[76:79], v[144:147], v[232:235], v[76:79]
	v_mfma_f32_16x16x32_bf16 v[80:83], v[136:139], v[232:235], v[80:83]
	v_mfma_f32_16x16x32_bf16 v[80:83], v[132:135], v[228:231], v[80:83]
	v_mfma_f32_16x16x32_bf16 v[120:123], v[176:179], v[194:197], v[120:123]
	v_mfma_f32_16x16x32_bf16 v[120:123], v[182:185], v[198:201], v[120:123]
	v_mfma_f32_16x16x32_bf16 v[116:119], v[190:193], v[198:201], v[116:119]
	v_mfma_f32_16x16x32_bf16 v[116:119], v[186:189], v[194:197], v[116:119]
	v_mfma_f32_16x16x32_bf16 v[100:103], v[186:189], v[202:205], v[100:103]
	v_mfma_f32_16x16x32_bf16 v[100:103], v[190:193], v[206:209], v[100:103]
	v_mfma_f32_16x16x32_bf16 v[104:107], v[182:185], v[206:209], v[104:107]
	v_mfma_f32_16x16x32_bf16 v[104:107], v[176:179], v[202:205], v[104:107]
	v_mfma_f32_16x16x32_bf16 v[88:91], v[176:179], v[210:213], v[88:91]
	v_mfma_f32_16x16x32_bf16 v[88:91], v[182:185], v[214:217], v[88:91]
	v_mfma_f32_16x16x32_bf16 v[84:87], v[190:193], v[214:217], v[84:87]
	v_mfma_f32_16x16x32_bf16 v[84:87], v[186:189], v[210:213], v[84:87]
	v_mfma_f32_16x16x32_bf16 v[68:71], v[186:189], v[228:231], v[68:71]
	v_mfma_f32_16x16x32_bf16 v[68:71], v[190:193], v[232:235], v[68:71]
	v_mfma_f32_16x16x32_bf16 v[72:75], v[182:185], v[232:235], v[72:75]
	v_mfma_f32_16x16x32_bf16 v[72:75], v[176:179], v[228:231], v[72:75]
	s_add_u32 s46, s34, 0x70000
	s_addc_u32 s47, s35, 0
	s_add_i32 s52, s52, s2
	s_mov_b32 m0, s52
	ds_read_b128 v[194:197], v181 offset:49152
	ds_read_b128 v[198:201], v181 offset:50176
	ds_read_b128 v[202:205], v181 offset:51200
	ds_read_b128 v[206:209], v181 offset:52224
	ds_read_b128 v[210:213], v181 offset:53248
	ds_read_b128 v[214:217], v181 offset:54272
	ds_read_b128 v[228:231], v181 offset:55296
	ds_read_b128 v[232:235], v181 offset:56320
	global_load_lds_dwordx4 v150, s[46:47]
	s_add_i32 m0, s52, 0x2000
	s_add_u32 s34, s34, 0x74000
	global_load_lds_dwordx4 v0, s[46:47]
	s_addc_u32 s35, s35, 0
	s_add_i32 s46, s53, s2
	s_mov_b32 m0, s46
	s_nop 0
	global_load_lds_dwordx4 v150, s[34:35]
	s_add_i32 m0, s46, 0x2000
	s_nop 0
	global_load_lds_dwordx4 v0, s[34:35]
	s_mov_b32 m0, s97
	s_nop 0
	global_load_lds_dwordx4 v152, s[100:101]
	s_mov_b32 m0, s76
	s_nop 0
	global_load_lds_dwordx4 v148, s[100:101]
	s_waitcnt vmcnt(8)
	s_waitcnt lgkmcnt(0)
	s_barrier
	s_setprio 2
	v_mfma_f32_16x16x32_bf16 v[64:67], v[132:135], v[194:197], v[64:67]
	v_mfma_f32_16x16x32_bf16 v[64:67], v[136:139], v[198:201], v[64:67]
	v_mfma_f32_16x16x32_bf16 v[60:63], v[144:147], v[198:201], v[60:63]
	v_mfma_f32_16x16x32_bf16 v[60:63], v[140:143], v[194:197], v[60:63]
	v_mfma_f32_16x16x32_bf16 v[44:47], v[140:143], v[202:205], v[44:47]
	v_mfma_f32_16x16x32_bf16 v[44:47], v[144:147], v[206:209], v[44:47]
	v_mfma_f32_16x16x32_bf16 v[48:51], v[136:139], v[206:209], v[48:51]
	v_mfma_f32_16x16x32_bf16 v[48:51], v[132:135], v[202:205], v[48:51]
	v_mfma_f32_16x16x32_bf16 v[32:35], v[132:135], v[210:213], v[32:35]
	v_mfma_f32_16x16x32_bf16 v[32:35], v[136:139], v[214:217], v[32:35]
	v_mfma_f32_16x16x32_bf16 v[28:31], v[144:147], v[214:217], v[28:31]
	v_mfma_f32_16x16x32_bf16 v[28:31], v[140:143], v[210:213], v[28:31]
	v_mfma_f32_16x16x32_bf16 v[12:15], v[140:143], v[228:231], v[12:15]
	v_mfma_f32_16x16x32_bf16 v[12:15], v[144:147], v[232:235], v[12:15]
	v_mfma_f32_16x16x32_bf16 v[16:19], v[136:139], v[232:235], v[16:19]
	v_mfma_f32_16x16x32_bf16 v[16:19], v[132:135], v[228:231], v[16:19]
	v_mfma_f32_16x16x32_bf16 v[56:59], v[176:179], v[194:197], v[56:59]
	v_mfma_f32_16x16x32_bf16 v[56:59], v[182:185], v[198:201], v[56:59]
	v_mfma_f32_16x16x32_bf16 v[52:55], v[190:193], v[198:201], v[52:55]
	v_mfma_f32_16x16x32_bf16 v[52:55], v[186:189], v[194:197], v[52:55]
	v_mfma_f32_16x16x32_bf16 v[36:39], v[186:189], v[202:205], v[36:39]
	v_mfma_f32_16x16x32_bf16 v[36:39], v[190:193], v[206:209], v[36:39]
	v_mfma_f32_16x16x32_bf16 v[40:43], v[182:185], v[206:209], v[40:43]
	v_mfma_f32_16x16x32_bf16 v[40:43], v[176:179], v[202:205], v[40:43]
	v_mfma_f32_16x16x32_bf16 v[24:27], v[176:179], v[210:213], v[24:27]
	v_mfma_f32_16x16x32_bf16 v[24:27], v[182:185], v[214:217], v[24:27]
	v_mfma_f32_16x16x32_bf16 v[20:23], v[190:193], v[214:217], v[20:23]
	v_mfma_f32_16x16x32_bf16 v[20:23], v[186:189], v[210:213], v[20:23]
	v_mfma_f32_16x16x32_bf16 v[4:7], v[186:189], v[228:231], v[4:7]
	v_mfma_f32_16x16x32_bf16 v[4:7], v[190:193], v[232:235], v[4:7]
	v_mfma_f32_16x16x32_bf16 v[8:11], v[182:185], v[232:235], v[8:11]
	v_mfma_f32_16x16x32_bf16 v[8:11], v[176:179], v[228:231], v[8:11]
	s_add_i32 vcc_hi, vcc_hi, 2
	s_add_u32 s63, s63, 0xe0000
	s_addc_u32 vcc_lo, vcc_lo, 0
	s_add_u32 s44, s44, 0x100
	s_addc_u32 s45, s45, 0
	s_cmp_gt_u32 vcc_hi, 29
	s_cbranch_scc0 .Ltrail_2

.LBB0_559:
	s_add_i32 vcc_lo, s34, 2
	s_add_u32 s35, s42, 0x80
	s_addc_u32 s52, s43, 0
	s_add_i32 s53, 0, 0x10000
	s_cmp_eq_u32 s77, s34
	s_cselect_b32 s57, s51, s52
	s_cselect_b32 s56, s50, s35
	s_cselect_b32 s35, s36, s97
	s_cselect_b32 s34, s37, s49
	s_add_i32 s68, 0, 0x14000
	v_add_u32_e32 v136, s53, v200
	v_add_u32_e32 v186, s68, v200
	ds_read_b128 v[116:119], v136
	ds_read_b128 v[120:123], v136 offset:1024
	ds_read_b128 v[124:127], v136 offset:2048
	ds_read_b128 v[136:139], v136 offset:3072
	ds_read_b128 v[148:151], v186
	ds_read_b128 v[152:155], v186 offset:1024
	ds_read_b128 v[182:185], v186 offset:2048
	ds_read_b128 v[186:189], v186 offset:3072
	s_add_i32 m0, s59, 0xc000
	ds_read_b128 v[190:193], v202
	ds_read_b128 v[194:197], v202 offset:1024
	ds_read_b128 v[204:207], v202 offset:2048
	ds_read_b128 v[208:211], v202 offset:3072
	ds_read_b128 v[212:215], v202 offset:4096
	ds_read_b128 v[216:219], v202 offset:5120
	ds_read_b128 v[228:231], v202 offset:6144
	ds_read_b128 v[232:235], v202 offset:7168
	global_load_lds_dwordx4 v178, s[42:43]
	s_add_i32 m0, s59, 0xe000
	s_nop 0
	global_load_lds_dwordx4 v180, s[42:43]
	s_waitcnt lgkmcnt(0)
	s_setprio 1
	v_mfma_f32_16x16x32_bf16 v[144:147], v[116:119], v[190:193], v[144:147]
	v_mfma_f32_16x16x32_bf16 v[144:147], v[120:123], v[194:197], v[144:147]
	v_mfma_f32_16x16x32_bf16 v[140:143], v[136:139], v[194:197], v[140:143]
	v_mfma_f32_16x16x32_bf16 v[140:143], v[124:127], v[190:193], v[140:143]
	v_mfma_f32_16x16x32_bf16 v[108:111], v[124:127], v[204:207], v[108:111]
	v_mfma_f32_16x16x32_bf16 v[108:111], v[136:139], v[208:211], v[108:111]
	v_mfma_f32_16x16x32_bf16 v[112:115], v[120:123], v[208:211], v[112:115]
	v_mfma_f32_16x16x32_bf16 v[112:115], v[116:119], v[204:207], v[112:115]
	v_mfma_f32_16x16x32_bf16 v[96:99], v[116:119], v[212:215], v[96:99]
	v_mfma_f32_16x16x32_bf16 v[96:99], v[120:123], v[216:219], v[96:99]
	v_mfma_f32_16x16x32_bf16 v[92:95], v[136:139], v[216:219], v[92:95]
	v_mfma_f32_16x16x32_bf16 v[92:95], v[124:127], v[212:215], v[92:95]
	v_mfma_f32_16x16x32_bf16 v[76:79], v[124:127], v[228:231], v[76:79]
	v_mfma_f32_16x16x32_bf16 v[76:79], v[136:139], v[232:235], v[76:79]
	v_mfma_f32_16x16x32_bf16 v[80:83], v[120:123], v[232:235], v[80:83]
	v_mfma_f32_16x16x32_bf16 v[80:83], v[116:119], v[228:231], v[80:83]
	v_mfma_f32_16x16x32_bf16 v[132:135], v[148:151], v[190:193], v[132:135]
	v_mfma_f32_16x16x32_bf16 v[132:135], v[152:155], v[194:197], v[132:135]
	v_mfma_f32_16x16x32_bf16 v[128:131], v[186:189], v[194:197], v[128:131]
	v_mfma_f32_16x16x32_bf16 v[128:131], v[182:185], v[190:193], v[128:131]
	v_mfma_f32_16x16x32_bf16 v[100:103], v[182:185], v[204:207], v[100:103]
	v_mfma_f32_16x16x32_bf16 v[100:103], v[186:189], v[208:211], v[100:103]
	v_mfma_f32_16x16x32_bf16 v[104:107], v[152:155], v[208:211], v[104:107]
	v_mfma_f32_16x16x32_bf16 v[104:107], v[148:151], v[204:207], v[104:107]
	v_mfma_f32_16x16x32_bf16 v[88:91], v[148:151], v[212:215], v[88:91]
	v_mfma_f32_16x16x32_bf16 v[88:91], v[152:155], v[216:219], v[88:91]
	v_mfma_f32_16x16x32_bf16 v[84:87], v[186:189], v[216:219], v[84:87]
	v_mfma_f32_16x16x32_bf16 v[84:87], v[182:185], v[212:215], v[84:87]
	v_mfma_f32_16x16x32_bf16 v[68:71], v[182:185], v[228:231], v[68:71]
	v_mfma_f32_16x16x32_bf16 v[68:71], v[186:189], v[232:235], v[68:71]
	v_mfma_f32_16x16x32_bf16 v[72:75], v[152:155], v[232:235], v[72:75]
	v_mfma_f32_16x16x32_bf16 v[72:75], v[148:151], v[228:231], v[72:75]
	s_waitcnt vmcnt(8)
	s_setprio 0
	s_barrier
	s_add_u32 s100, s56, s14
	s_addc_u32 s101, s57, s15
	s_add_i32 s52, s53, s58
	s_mov_b32 m0, s52
	ds_read_b128 v[190:193], v202 offset:16384
	ds_read_b128 v[194:197], v202 offset:17408
	ds_read_b128 v[204:207], v202 offset:18432
	ds_read_b128 v[208:211], v202 offset:19456
	ds_read_b128 v[212:215], v202 offset:20480
	ds_read_b128 v[216:219], v202 offset:21504
	ds_read_b128 v[228:231], v202 offset:22528
	ds_read_b128 v[232:235], v202 offset:23552
	global_load_lds_dwordx4 v174, s[34:35]
	s_add_i32 m0, s52, 0x2000
	s_add_u32 s52, s34, 0x4000
	s_addc_u32 s53, s35, 0
	s_add_i32 s68, s68, s58
	global_load_lds_dwordx4 v0, s[34:35]
	s_mov_b32 m0, s68
	s_nop 0
	global_load_lds_dwordx4 v174, s[52:53]
	s_add_i32 m0, s68, 0x2000
	s_nop 0
	global_load_lds_dwordx4 v0, s[52:53]
	s_mov_b32 m0, s59
	s_nop 0
	global_load_lds_dwordx4 v176, s[56:57]
	s_mov_b32 m0, s60
	s_nop 0
	global_load_lds_dwordx4 v172, s[56:57]
	s_waitcnt lgkmcnt(0)
	s_setprio 1
	v_mfma_f32_16x16x32_bf16 v[64:67], v[116:119], v[190:193], v[64:67]
	v_mfma_f32_16x16x32_bf16 v[64:67], v[120:123], v[194:197], v[64:67]
	v_mfma_f32_16x16x32_bf16 v[60:63], v[136:139], v[194:197], v[60:63]
	v_mfma_f32_16x16x32_bf16 v[60:63], v[124:127], v[190:193], v[60:63]
	v_mfma_f32_16x16x32_bf16 v[44:47], v[124:127], v[204:207], v[44:47]
	v_mfma_f32_16x16x32_bf16 v[44:47], v[136:139], v[208:211], v[44:47]
	v_mfma_f32_16x16x32_bf16 v[48:51], v[120:123], v[208:211], v[48:51]
	v_mfma_f32_16x16x32_bf16 v[48:51], v[116:119], v[204:207], v[48:51]
	v_mfma_f32_16x16x32_bf16 v[32:35], v[116:119], v[212:215], v[32:35]
	v_mfma_f32_16x16x32_bf16 v[32:35], v[120:123], v[216:219], v[32:35]
	v_mfma_f32_16x16x32_bf16 v[28:31], v[136:139], v[216:219], v[28:31]
	v_mfma_f32_16x16x32_bf16 v[28:31], v[124:127], v[212:215], v[28:31]
	v_mfma_f32_16x16x32_bf16 v[12:15], v[124:127], v[228:231], v[12:15]
	v_mfma_f32_16x16x32_bf16 v[12:15], v[136:139], v[232:235], v[12:15]
	v_mfma_f32_16x16x32_bf16 v[16:19], v[120:123], v[232:235], v[16:19]
	v_mfma_f32_16x16x32_bf16 v[16:19], v[116:119], v[228:231], v[16:19]
	v_mfma_f32_16x16x32_bf16 v[56:59], v[148:151], v[190:193], v[56:59]
	v_mfma_f32_16x16x32_bf16 v[56:59], v[152:155], v[194:197], v[56:59]
	v_mfma_f32_16x16x32_bf16 v[52:55], v[186:189], v[194:197], v[52:55]
	v_mfma_f32_16x16x32_bf16 v[52:55], v[182:185], v[190:193], v[52:55]
	v_mfma_f32_16x16x32_bf16 v[36:39], v[182:185], v[204:207], v[36:39]
	v_mfma_f32_16x16x32_bf16 v[36:39], v[186:189], v[208:211], v[36:39]
	v_mfma_f32_16x16x32_bf16 v[40:43], v[152:155], v[208:211], v[40:43]
	v_mfma_f32_16x16x32_bf16 v[40:43], v[148:151], v[204:207], v[40:43]
	v_mfma_f32_16x16x32_bf16 v[24:27], v[148:151], v[212:215], v[24:27]
	v_mfma_f32_16x16x32_bf16 v[24:27], v[152:155], v[216:219], v[24:27]
	v_mfma_f32_16x16x32_bf16 v[20:23], v[186:189], v[216:219], v[20:23]
	v_mfma_f32_16x16x32_bf16 v[20:23], v[182:185], v[212:215], v[20:23]
	v_mfma_f32_16x16x32_bf16 v[4:7], v[182:185], v[228:231], v[4:7]
	v_mfma_f32_16x16x32_bf16 v[4:7], v[186:189], v[232:235], v[4:7]
	v_mfma_f32_16x16x32_bf16 v[8:11], v[152:155], v[232:235], v[8:11]
	v_mfma_f32_16x16x32_bf16 v[8:11], v[148:151], v[228:231], v[8:11]
	s_waitcnt vmcnt(8)
	s_setprio 0
	s_barrier
	s_add_i32 s68, 0, 0x18000
	s_add_i32 vcc_hi, 0, 0x1c000
	v_add_u32_e32 v136, s68, v200
	v_add_u32_e32 v186, vcc_hi, v200
	ds_read_b128 v[116:119], v136
	ds_read_b128 v[120:123], v136 offset:1024
	ds_read_b128 v[124:127], v136 offset:2048
	ds_read_b128 v[136:139], v136 offset:3072
	ds_read_b128 v[148:151], v186
	ds_read_b128 v[152:155], v186 offset:1024
	ds_read_b128 v[182:185], v186 offset:2048
	ds_read_b128 v[186:189], v186 offset:3072
	s_add_u32 s52, s56, s26
	s_addc_u32 s53, s57, 0
	s_mov_b32 m0, s61
	ds_read_b128 v[190:193], v202 offset:32768
	ds_read_b128 v[194:197], v202 offset:33792
	ds_read_b128 v[204:207], v202 offset:34816
	ds_read_b128 v[208:211], v202 offset:35840
	ds_read_b128 v[212:215], v202 offset:36864
	ds_read_b128 v[216:219], v202 offset:37888
	ds_read_b128 v[228:231], v202 offset:38912
	ds_read_b128 v[232:235], v202 offset:39936
	global_load_lds_dwordx4 v176, s[52:53]
	s_mov_b32 m0, s62
	s_nop 0
	global_load_lds_dwordx4 v172, s[52:53]
	s_waitcnt lgkmcnt(0)
	s_setprio 1
	v_mfma_f32_16x16x32_bf16 v[144:147], v[116:119], v[190:193], v[144:147]
	v_mfma_f32_16x16x32_bf16 v[144:147], v[120:123], v[194:197], v[144:147]
	v_mfma_f32_16x16x32_bf16 v[140:143], v[136:139], v[194:197], v[140:143]
	v_mfma_f32_16x16x32_bf16 v[140:143], v[124:127], v[190:193], v[140:143]
	v_mfma_f32_16x16x32_bf16 v[108:111], v[124:127], v[204:207], v[108:111]
	v_mfma_f32_16x16x32_bf16 v[108:111], v[136:139], v[208:211], v[108:111]
	v_mfma_f32_16x16x32_bf16 v[112:115], v[120:123], v[208:211], v[112:115]
	v_mfma_f32_16x16x32_bf16 v[112:115], v[116:119], v[204:207], v[112:115]
	v_mfma_f32_16x16x32_bf16 v[96:99], v[116:119], v[212:215], v[96:99]
	v_mfma_f32_16x16x32_bf16 v[96:99], v[120:123], v[216:219], v[96:99]
	v_mfma_f32_16x16x32_bf16 v[92:95], v[136:139], v[216:219], v[92:95]
	v_mfma_f32_16x16x32_bf16 v[92:95], v[124:127], v[212:215], v[92:95]
	v_mfma_f32_16x16x32_bf16 v[76:79], v[124:127], v[228:231], v[76:79]
	v_mfma_f32_16x16x32_bf16 v[76:79], v[136:139], v[232:235], v[76:79]
	v_mfma_f32_16x16x32_bf16 v[80:83], v[120:123], v[232:235], v[80:83]
	v_mfma_f32_16x16x32_bf16 v[80:83], v[116:119], v[228:231], v[80:83]
	v_mfma_f32_16x16x32_bf16 v[132:135], v[148:151], v[190:193], v[132:135]
	v_mfma_f32_16x16x32_bf16 v[132:135], v[152:155], v[194:197], v[132:135]
	v_mfma_f32_16x16x32_bf16 v[128:131], v[186:189], v[194:197], v[128:131]
	v_mfma_f32_16x16x32_bf16 v[128:131], v[182:185], v[190:193], v[128:131]
	v_mfma_f32_16x16x32_bf16 v[100:103], v[182:185], v[204:207], v[100:103]
	v_mfma_f32_16x16x32_bf16 v[100:103], v[186:189], v[208:211], v[100:103]
	v_mfma_f32_16x16x32_bf16 v[104:107], v[152:155], v[208:211], v[104:107]
	v_mfma_f32_16x16x32_bf16 v[104:107], v[148:151], v[204:207], v[104:107]
	v_mfma_f32_16x16x32_bf16 v[88:91], v[148:151], v[212:215], v[88:91]
	v_mfma_f32_16x16x32_bf16 v[88:91], v[152:155], v[216:219], v[88:91]
	v_mfma_f32_16x16x32_bf16 v[84:87], v[186:189], v[216:219], v[84:87]
	v_mfma_f32_16x16x32_bf16 v[84:87], v[182:185], v[212:215], v[84:87]
	v_mfma_f32_16x16x32_bf16 v[68:71], v[182:185], v[228:231], v[68:71]
	v_mfma_f32_16x16x32_bf16 v[68:71], v[186:189], v[232:235], v[68:71]
	v_mfma_f32_16x16x32_bf16 v[72:75], v[152:155], v[232:235], v[72:75]
	v_mfma_f32_16x16x32_bf16 v[72:75], v[148:151], v[228:231], v[72:75]
	s_waitcnt vmcnt(8)
	s_setprio 0
	s_barrier
	s_add_u32 s52, s34, 0x40000
	s_addc_u32 s53, s35, 0
	s_add_i32 s56, s68, s58
	s_mov_b32 m0, s56
	ds_read_b128 v[190:193], v202 offset:49152
	ds_read_b128 v[194:197], v202 offset:50176
	ds_read_b128 v[204:207], v202 offset:51200
	ds_read_b128 v[208:211], v202 offset:52224
	ds_read_b128 v[212:215], v202 offset:53248
	ds_read_b128 v[216:219], v202 offset:54272
	ds_read_b128 v[228:231], v202 offset:55296
	ds_read_b128 v[232:235], v202 offset:56320
	global_load_lds_dwordx4 v174, s[52:53]
	s_add_i32 m0, s56, 0x2000
	s_add_u32 s34, s34, 0x44000
	global_load_lds_dwordx4 v0, s[52:53]
	s_addc_u32 s35, s35, 0
	s_add_i32 s52, vcc_hi, s58
	s_mov_b32 m0, s52
	s_nop 0
	global_load_lds_dwordx4 v174, s[34:35]
	s_add_i32 m0, s52, 0x2000
	s_nop 0
	global_load_lds_dwordx4 v0, s[34:35]
	s_mov_b32 m0, s71
	s_nop 0
	global_load_lds_dwordx4 v176, s[100:101]
	s_mov_b32 m0, s76
	s_nop 0
	global_load_lds_dwordx4 v172, s[100:101]
	s_waitcnt lgkmcnt(0)
	s_setprio 1
	v_mfma_f32_16x16x32_bf16 v[64:67], v[116:119], v[190:193], v[64:67]
	v_mfma_f32_16x16x32_bf16 v[64:67], v[120:123], v[194:197], v[64:67]
	v_mfma_f32_16x16x32_bf16 v[60:63], v[136:139], v[194:197], v[60:63]
	v_mfma_f32_16x16x32_bf16 v[60:63], v[124:127], v[190:193], v[60:63]
	v_mfma_f32_16x16x32_bf16 v[44:47], v[124:127], v[204:207], v[44:47]
	v_mfma_f32_16x16x32_bf16 v[44:47], v[136:139], v[208:211], v[44:47]
	v_mfma_f32_16x16x32_bf16 v[48:51], v[120:123], v[208:211], v[48:51]
	v_mfma_f32_16x16x32_bf16 v[48:51], v[116:119], v[204:207], v[48:51]
	v_mfma_f32_16x16x32_bf16 v[32:35], v[116:119], v[212:215], v[32:35]
	v_mfma_f32_16x16x32_bf16 v[32:35], v[120:123], v[216:219], v[32:35]
	v_mfma_f32_16x16x32_bf16 v[28:31], v[136:139], v[216:219], v[28:31]
	v_mfma_f32_16x16x32_bf16 v[28:31], v[124:127], v[212:215], v[28:31]
	v_mfma_f32_16x16x32_bf16 v[12:15], v[124:127], v[228:231], v[12:15]
	v_mfma_f32_16x16x32_bf16 v[12:15], v[136:139], v[232:235], v[12:15]
	v_mfma_f32_16x16x32_bf16 v[16:19], v[120:123], v[232:235], v[16:19]
	v_mfma_f32_16x16x32_bf16 v[16:19], v[116:119], v[228:231], v[16:19]
	v_mfma_f32_16x16x32_bf16 v[56:59], v[148:151], v[190:193], v[56:59]
	v_mfma_f32_16x16x32_bf16 v[56:59], v[152:155], v[194:197], v[56:59]
	v_mfma_f32_16x16x32_bf16 v[52:55], v[186:189], v[194:197], v[52:55]
	v_mfma_f32_16x16x32_bf16 v[52:55], v[182:185], v[190:193], v[52:55]
	v_mfma_f32_16x16x32_bf16 v[36:39], v[182:185], v[204:207], v[36:39]
	v_mfma_f32_16x16x32_bf16 v[36:39], v[186:189], v[208:211], v[36:39]
	v_mfma_f32_16x16x32_bf16 v[40:43], v[152:155], v[208:211], v[40:43]
	v_mfma_f32_16x16x32_bf16 v[40:43], v[148:151], v[204:207], v[40:43]
	v_mfma_f32_16x16x32_bf16 v[24:27], v[148:151], v[212:215], v[24:27]
	v_mfma_f32_16x16x32_bf16 v[24:27], v[152:155], v[216:219], v[24:27]
	v_mfma_f32_16x16x32_bf16 v[20:23], v[186:189], v[216:219], v[20:23]
	v_mfma_f32_16x16x32_bf16 v[20:23], v[182:185], v[212:215], v[20:23]
	v_mfma_f32_16x16x32_bf16 v[4:7], v[182:185], v[228:231], v[4:7]
	v_mfma_f32_16x16x32_bf16 v[4:7], v[186:189], v[232:235], v[4:7]
	v_mfma_f32_16x16x32_bf16 v[8:11], v[152:155], v[232:235], v[8:11]
	v_mfma_f32_16x16x32_bf16 v[8:11], v[148:151], v[228:231], v[8:11]
	s_waitcnt vmcnt(8)
	s_setprio 0
	s_barrier
	s_add_u32 s49, s49, 0x80000
	s_addc_u32 s97, s97, 0
	s_add_u32 s42, s42, 0x100
	s_addc_u32 s43, s43, 0
	s_cmp_ge_u32 vcc_lo, s69
	s_mov_b32 s34, vcc_lo
	s_cbranch_scc0 .LBB0_559
	s_branch .Lkdone_3
.Ltrail_3:
	s_add_i32 vcc_lo, s34, 2
	s_add_u32 s35, s42, 0x80
	s_addc_u32 s52, s43, 0
	s_add_i32 s53, 0, 0x10000
	s_cmp_eq_u32 s77, s34
	s_cselect_b32 s57, s51, s52
	s_cselect_b32 s56, s50, s35
	s_cselect_b32 s35, s36, s97
	s_cselect_b32 s34, s37, s49
	s_add_i32 s68, 0, 0x14000
	v_add_u32_e32 v136, s53, v200
	v_add_u32_e32 v186, s68, v200
	ds_read_b128 v[116:119], v136
	ds_read_b128 v[120:123], v136 offset:1024
	ds_read_b128 v[124:127], v136 offset:2048
	ds_read_b128 v[136:139], v136 offset:3072
	ds_read_b128 v[148:151], v186
	ds_read_b128 v[152:155], v186 offset:1024
	ds_read_b128 v[182:185], v186 offset:2048
	ds_read_b128 v[186:189], v186 offset:3072
	s_add_i32 m0, s59, 0xc000
	ds_read_b128 v[190:193], v202
	ds_read_b128 v[194:197], v202 offset:1024
	ds_read_b128 v[204:207], v202 offset:2048
	ds_read_b128 v[208:211], v202 offset:3072
	ds_read_b128 v[212:215], v202 offset:4096
	ds_read_b128 v[216:219], v202 offset:5120
	ds_read_b128 v[228:231], v202 offset:6144
	ds_read_b128 v[232:235], v202 offset:7168
	global_load_lds_dwordx4 v178, s[42:43]
	s_add_i32 m0, s59, 0xe000
	s_nop 0
	global_load_lds_dwordx4 v180, s[42:43]
	s_waitcnt vmcnt(8)
	s_waitcnt lgkmcnt(0)
	s_barrier
	s_setprio 2
	v_mfma_f32_16x16x32_bf16 v[144:147], v[116:119], v[190:193], v[144:147]
	v_mfma_f32_16x16x32_bf16 v[144:147], v[120:123], v[194:197], v[144:147]
	v_mfma_f32_16x16x32_bf16 v[140:143], v[136:139], v[194:197], v[140:143]
	v_mfma_f32_16x16x32_bf16 v[140:143], v[124:127], v[190:193], v[140:143]
	v_mfma_f32_16x16x32_bf16 v[108:111], v[124:127], v[204:207], v[108:111]
	v_mfma_f32_16x16x32_bf16 v[108:111], v[136:139], v[208:211], v[108:111]
	v_mfma_f32_16x16x32_bf16 v[112:115], v[120:123], v[208:211], v[112:115]
	v_mfma_f32_16x16x32_bf16 v[112:115], v[116:119], v[204:207], v[112:115]
	v_mfma_f32_16x16x32_bf16 v[96:99], v[116:119], v[212:215], v[96:99]
	v_mfma_f32_16x16x32_bf16 v[96:99], v[120:123], v[216:219], v[96:99]
	v_mfma_f32_16x16x32_bf16 v[92:95], v[136:139], v[216:219], v[92:95]
	v_mfma_f32_16x16x32_bf16 v[92:95], v[124:127], v[212:215], v[92:95]
	v_mfma_f32_16x16x32_bf16 v[76:79], v[124:127], v[228:231], v[76:79]
	v_mfma_f32_16x16x32_bf16 v[76:79], v[136:139], v[232:235], v[76:79]
	v_mfma_f32_16x16x32_bf16 v[80:83], v[120:123], v[232:235], v[80:83]
	v_mfma_f32_16x16x32_bf16 v[80:83], v[116:119], v[228:231], v[80:83]
	v_mfma_f32_16x16x32_bf16 v[132:135], v[148:151], v[190:193], v[132:135]
	v_mfma_f32_16x16x32_bf16 v[132:135], v[152:155], v[194:197], v[132:135]
	v_mfma_f32_16x16x32_bf16 v[128:131], v[186:189], v[194:197], v[128:131]
	v_mfma_f32_16x16x32_bf16 v[128:131], v[182:185], v[190:193], v[128:131]
	v_mfma_f32_16x16x32_bf16 v[100:103], v[182:185], v[204:207], v[100:103]
	v_mfma_f32_16x16x32_bf16 v[100:103], v[186:189], v[208:211], v[100:103]
	v_mfma_f32_16x16x32_bf16 v[104:107], v[152:155], v[208:211], v[104:107]
	v_mfma_f32_16x16x32_bf16 v[104:107], v[148:151], v[204:207], v[104:107]
	v_mfma_f32_16x16x32_bf16 v[88:91], v[148:151], v[212:215], v[88:91]
	v_mfma_f32_16x16x32_bf16 v[88:91], v[152:155], v[216:219], v[88:91]
	v_mfma_f32_16x16x32_bf16 v[84:87], v[186:189], v[216:219], v[84:87]
	v_mfma_f32_16x16x32_bf16 v[84:87], v[182:185], v[212:215], v[84:87]
	v_mfma_f32_16x16x32_bf16 v[68:71], v[182:185], v[228:231], v[68:71]
	v_mfma_f32_16x16x32_bf16 v[68:71], v[186:189], v[232:235], v[68:71]
	v_mfma_f32_16x16x32_bf16 v[72:75], v[152:155], v[232:235], v[72:75]
	v_mfma_f32_16x16x32_bf16 v[72:75], v[148:151], v[228:231], v[72:75]
	s_add_u32 s100, s56, s14
	s_addc_u32 s101, s57, s15
	s_add_i32 s52, s53, s58
	s_mov_b32 m0, s52
	ds_read_b128 v[190:193], v202 offset:16384
	ds_read_b128 v[194:197], v202 offset:17408
	ds_read_b128 v[204:207], v202 offset:18432
	ds_read_b128 v[208:211], v202 offset:19456
	ds_read_b128 v[212:215], v202 offset:20480
	ds_read_b128 v[216:219], v202 offset:21504
	ds_read_b128 v[228:231], v202 offset:22528
	ds_read_b128 v[232:235], v202 offset:23552
	global_load_lds_dwordx4 v174, s[34:35]
	s_add_i32 m0, s52, 0x2000
	s_add_u32 s52, s34, 0x4000
	s_addc_u32 s53, s35, 0
	s_add_i32 s68, s68, s58
	global_load_lds_dwordx4 v0, s[34:35]
	s_mov_b32 m0, s68
	s_nop 0
	global_load_lds_dwordx4 v174, s[52:53]
	s_add_i32 m0, s68, 0x2000
	s_nop 0
	global_load_lds_dwordx4 v0, s[52:53]
	s_mov_b32 m0, s59
	s_nop 0
	global_load_lds_dwordx4 v176, s[56:57]
	s_mov_b32 m0, s60
	s_nop 0
	global_load_lds_dwordx4 v172, s[56:57]
	s_waitcnt vmcnt(8)
	s_waitcnt lgkmcnt(0)
	s_barrier
	s_setprio 2
	v_mfma_f32_16x16x32_bf16 v[64:67], v[116:119], v[190:193], v[64:67]
	v_mfma_f32_16x16x32_bf16 v[64:67], v[120:123], v[194:197], v[64:67]
	v_mfma_f32_16x16x32_bf16 v[60:63], v[136:139], v[194:197], v[60:63]
	v_mfma_f32_16x16x32_bf16 v[60:63], v[124:127], v[190:193], v[60:63]
	v_mfma_f32_16x16x32_bf16 v[44:47], v[124:127], v[204:207], v[44:47]
	v_mfma_f32_16x16x32_bf16 v[44:47], v[136:139], v[208:211], v[44:47]
	v_mfma_f32_16x16x32_bf16 v[48:51], v[120:123], v[208:211], v[48:51]
	v_mfma_f32_16x16x32_bf16 v[48:51], v[116:119], v[204:207], v[48:51]
	v_mfma_f32_16x16x32_bf16 v[32:35], v[116:119], v[212:215], v[32:35]
	v_mfma_f32_16x16x32_bf16 v[32:35], v[120:123], v[216:219], v[32:35]
	v_mfma_f32_16x16x32_bf16 v[28:31], v[136:139], v[216:219], v[28:31]
	v_mfma_f32_16x16x32_bf16 v[28:31], v[124:127], v[212:215], v[28:31]
	v_mfma_f32_16x16x32_bf16 v[12:15], v[124:127], v[228:231], v[12:15]
	v_mfma_f32_16x16x32_bf16 v[12:15], v[136:139], v[232:235], v[12:15]
	v_mfma_f32_16x16x32_bf16 v[16:19], v[120:123], v[232:235], v[16:19]
	v_mfma_f32_16x16x32_bf16 v[16:19], v[116:119], v[228:231], v[16:19]
	v_mfma_f32_16x16x32_bf16 v[56:59], v[148:151], v[190:193], v[56:59]
	v_mfma_f32_16x16x32_bf16 v[56:59], v[152:155], v[194:197], v[56:59]
	v_mfma_f32_16x16x32_bf16 v[52:55], v[186:189], v[194:197], v[52:55]
	v_mfma_f32_16x16x32_bf16 v[52:55], v[182:185], v[190:193], v[52:55]
	v_mfma_f32_16x16x32_bf16 v[36:39], v[182:185], v[204:207], v[36:39]
	v_mfma_f32_16x16x32_bf16 v[36:39], v[186:189], v[208:211], v[36:39]
	v_mfma_f32_16x16x32_bf16 v[40:43], v[152:155], v[208:211], v[40:43]
	v_mfma_f32_16x16x32_bf16 v[40:43], v[148:151], v[204:207], v[40:43]
	v_mfma_f32_16x16x32_bf16 v[24:27], v[148:151], v[212:215], v[24:27]
	v_mfma_f32_16x16x32_bf16 v[24:27], v[152:155], v[216:219], v[24:27]
	v_mfma_f32_16x16x32_bf16 v[20:23], v[186:189], v[216:219], v[20:23]
	v_mfma_f32_16x16x32_bf16 v[20:23], v[182:185], v[212:215], v[20:23]
	v_mfma_f32_16x16x32_bf16 v[4:7], v[182:185], v[228:231], v[4:7]
	v_mfma_f32_16x16x32_bf16 v[4:7], v[186:189], v[232:235], v[4:7]
	v_mfma_f32_16x16x32_bf16 v[8:11], v[152:155], v[232:235], v[8:11]
	v_mfma_f32_16x16x32_bf16 v[8:11], v[148:151], v[228:231], v[8:11]
	s_add_i32 s68, 0, 0x18000
	s_add_i32 vcc_hi, 0, 0x1c000
	v_add_u32_e32 v136, s68, v200
	v_add_u32_e32 v186, vcc_hi, v200
	ds_read_b128 v[116:119], v136
	ds_read_b128 v[120:123], v136 offset:1024
	ds_read_b128 v[124:127], v136 offset:2048
	ds_read_b128 v[136:139], v136 offset:3072
	ds_read_b128 v[148:151], v186
	ds_read_b128 v[152:155], v186 offset:1024
	ds_read_b128 v[182:185], v186 offset:2048
	ds_read_b128 v[186:189], v186 offset:3072
	s_add_u32 s52, s56, s26
	s_addc_u32 s53, s57, 0
	s_mov_b32 m0, s61
	ds_read_b128 v[190:193], v202 offset:32768
	ds_read_b128 v[194:197], v202 offset:33792
	ds_read_b128 v[204:207], v202 offset:34816
	ds_read_b128 v[208:211], v202 offset:35840
	ds_read_b128 v[212:215], v202 offset:36864
	ds_read_b128 v[216:219], v202 offset:37888
	ds_read_b128 v[228:231], v202 offset:38912
	ds_read_b128 v[232:235], v202 offset:39936
	global_load_lds_dwordx4 v176, s[52:53]
	s_mov_b32 m0, s62
	s_nop 0
	global_load_lds_dwordx4 v172, s[52:53]
	s_waitcnt vmcnt(8)
	s_waitcnt lgkmcnt(0)
	s_barrier
	s_setprio 2
	v_mfma_f32_16x16x32_bf16 v[144:147], v[116:119], v[190:193], v[144:147]
	v_mfma_f32_16x16x32_bf16 v[144:147], v[120:123], v[194:197], v[144:147]
	v_mfma_f32_16x16x32_bf16 v[140:143], v[136:139], v[194:197], v[140:143]
	v_mfma_f32_16x16x32_bf16 v[140:143], v[124:127], v[190:193], v[140:143]
	v_mfma_f32_16x16x32_bf16 v[108:111], v[124:127], v[204:207], v[108:111]
	v_mfma_f32_16x16x32_bf16 v[108:111], v[136:139], v[208:211], v[108:111]
	v_mfma_f32_16x16x32_bf16 v[112:115], v[120:123], v[208:211], v[112:115]
	v_mfma_f32_16x16x32_bf16 v[112:115], v[116:119], v[204:207], v[112:115]
	v_mfma_f32_16x16x32_bf16 v[96:99], v[116:119], v[212:215], v[96:99]
	v_mfma_f32_16x16x32_bf16 v[96:99], v[120:123], v[216:219], v[96:99]
	v_mfma_f32_16x16x32_bf16 v[92:95], v[136:139], v[216:219], v[92:95]
	v_mfma_f32_16x16x32_bf16 v[92:95], v[124:127], v[212:215], v[92:95]
	v_mfma_f32_16x16x32_bf16 v[76:79], v[124:127], v[228:231], v[76:79]
	v_mfma_f32_16x16x32_bf16 v[76:79], v[136:139], v[232:235], v[76:79]
	v_mfma_f32_16x16x32_bf16 v[80:83], v[120:123], v[232:235], v[80:83]
	v_mfma_f32_16x16x32_bf16 v[80:83], v[116:119], v[228:231], v[80:83]
	v_mfma_f32_16x16x32_bf16 v[132:135], v[148:151], v[190:193], v[132:135]
	v_mfma_f32_16x16x32_bf16 v[132:135], v[152:155], v[194:197], v[132:135]
	v_mfma_f32_16x16x32_bf16 v[128:131], v[186:189], v[194:197], v[128:131]
	v_mfma_f32_16x16x32_bf16 v[128:131], v[182:185], v[190:193], v[128:131]
	v_mfma_f32_16x16x32_bf16 v[100:103], v[182:185], v[204:207], v[100:103]
	v_mfma_f32_16x16x32_bf16 v[100:103], v[186:189], v[208:211], v[100:103]
	v_mfma_f32_16x16x32_bf16 v[104:107], v[152:155], v[208:211], v[104:107]
	v_mfma_f32_16x16x32_bf16 v[104:107], v[148:151], v[204:207], v[104:107]
	v_mfma_f32_16x16x32_bf16 v[88:91], v[148:151], v[212:215], v[88:91]
	v_mfma_f32_16x16x32_bf16 v[88:91], v[152:155], v[216:219], v[88:91]
	v_mfma_f32_16x16x32_bf16 v[84:87], v[186:189], v[216:219], v[84:87]
	v_mfma_f32_16x16x32_bf16 v[84:87], v[182:185], v[212:215], v[84:87]
	v_mfma_f32_16x16x32_bf16 v[68:71], v[182:185], v[228:231], v[68:71]
	v_mfma_f32_16x16x32_bf16 v[68:71], v[186:189], v[232:235], v[68:71]
	v_mfma_f32_16x16x32_bf16 v[72:75], v[152:155], v[232:235], v[72:75]
	v_mfma_f32_16x16x32_bf16 v[72:75], v[148:151], v[228:231], v[72:75]
	s_add_u32 s52, s34, 0x40000
	s_addc_u32 s53, s35, 0
	s_add_i32 s56, s68, s58
	s_mov_b32 m0, s56
	ds_read_b128 v[190:193], v202 offset:49152
	ds_read_b128 v[194:197], v202 offset:50176
	ds_read_b128 v[204:207], v202 offset:51200
	ds_read_b128 v[208:211], v202 offset:52224
	ds_read_b128 v[212:215], v202 offset:53248
	ds_read_b128 v[216:219], v202 offset:54272
	ds_read_b128 v[228:231], v202 offset:55296
	ds_read_b128 v[232:235], v202 offset:56320
	global_load_lds_dwordx4 v174, s[52:53]
	s_add_i32 m0, s56, 0x2000
	s_add_u32 s34, s34, 0x44000
	global_load_lds_dwordx4 v0, s[52:53]
	s_addc_u32 s35, s35, 0
	s_add_i32 s52, vcc_hi, s58
	s_mov_b32 m0, s52
	s_nop 0
	global_load_lds_dwordx4 v174, s[34:35]
	s_add_i32 m0, s52, 0x2000
	s_nop 0
	global_load_lds_dwordx4 v0, s[34:35]
	s_mov_b32 m0, s71
	s_nop 0
	global_load_lds_dwordx4 v176, s[100:101]
	s_mov_b32 m0, s76
	s_nop 0
	global_load_lds_dwordx4 v172, s[100:101]
	s_waitcnt vmcnt(8)
	s_waitcnt lgkmcnt(0)
	s_barrier
	s_setprio 2
	v_mfma_f32_16x16x32_bf16 v[64:67], v[116:119], v[190:193], v[64:67]
	v_mfma_f32_16x16x32_bf16 v[64:67], v[120:123], v[194:197], v[64:67]
	v_mfma_f32_16x16x32_bf16 v[60:63], v[136:139], v[194:197], v[60:63]
	v_mfma_f32_16x16x32_bf16 v[60:63], v[124:127], v[190:193], v[60:63]
	v_mfma_f32_16x16x32_bf16 v[44:47], v[124:127], v[204:207], v[44:47]
	v_mfma_f32_16x16x32_bf16 v[44:47], v[136:139], v[208:211], v[44:47]
	v_mfma_f32_16x16x32_bf16 v[48:51], v[120:123], v[208:211], v[48:51]
	v_mfma_f32_16x16x32_bf16 v[48:51], v[116:119], v[204:207], v[48:51]
	v_mfma_f32_16x16x32_bf16 v[32:35], v[116:119], v[212:215], v[32:35]
	v_mfma_f32_16x16x32_bf16 v[32:35], v[120:123], v[216:219], v[32:35]
	v_mfma_f32_16x16x32_bf16 v[28:31], v[136:139], v[216:219], v[28:31]
	v_mfma_f32_16x16x32_bf16 v[28:31], v[124:127], v[212:215], v[28:31]
	v_mfma_f32_16x16x32_bf16 v[12:15], v[124:127], v[228:231], v[12:15]
	v_mfma_f32_16x16x32_bf16 v[12:15], v[136:139], v[232:235], v[12:15]
	v_mfma_f32_16x16x32_bf16 v[16:19], v[120:123], v[232:235], v[16:19]
	v_mfma_f32_16x16x32_bf16 v[16:19], v[116:119], v[228:231], v[16:19]
	v_mfma_f32_16x16x32_bf16 v[56:59], v[148:151], v[190:193], v[56:59]
	v_mfma_f32_16x16x32_bf16 v[56:59], v[152:155], v[194:197], v[56:59]
	v_mfma_f32_16x16x32_bf16 v[52:55], v[186:189], v[194:197], v[52:55]
	v_mfma_f32_16x16x32_bf16 v[52:55], v[182:185], v[190:193], v[52:55]
	v_mfma_f32_16x16x32_bf16 v[36:39], v[182:185], v[204:207], v[36:39]
	v_mfma_f32_16x16x32_bf16 v[36:39], v[186:189], v[208:211], v[36:39]
	v_mfma_f32_16x16x32_bf16 v[40:43], v[152:155], v[208:211], v[40:43]
	v_mfma_f32_16x16x32_bf16 v[40:43], v[148:151], v[204:207], v[40:43]
	v_mfma_f32_16x16x32_bf16 v[24:27], v[148:151], v[212:215], v[24:27]
	v_mfma_f32_16x16x32_bf16 v[24:27], v[152:155], v[216:219], v[24:27]
	v_mfma_f32_16x16x32_bf16 v[20:23], v[186:189], v[216:219], v[20:23]
	v_mfma_f32_16x16x32_bf16 v[20:23], v[182:185], v[212:215], v[20:23]
	v_mfma_f32_16x16x32_bf16 v[4:7], v[182:185], v[228:231], v[4:7]
	v_mfma_f32_16x16x32_bf16 v[4:7], v[186:189], v[232:235], v[4:7]
	v_mfma_f32_16x16x32_bf16 v[8:11], v[152:155], v[232:235], v[8:11]
	v_mfma_f32_16x16x32_bf16 v[8:11], v[148:151], v[228:231], v[8:11]
	s_add_u32 s49, s49, 0x80000
	s_addc_u32 s97, s97, 0
	s_add_u32 s42, s42, 0x100
	s_addc_u32 s43, s43, 0
	s_cmp_ge_u32 vcc_lo, s69
	s_mov_b32 s34, vcc_lo
	s_cbranch_scc0 .Ltrail_3
.Lkdone_3:
	s_setprio 0
	s_and_b64 vcc, exec, s[46:47]
	s_nop 0
	s_barrier
